# v16 + removed the redundant s_setprio 0/s_setprio 1 pair in the middle of each 32-MFMA block of the GEMM K-loops (24 sites)
# speedup vs baseline: 1.0087x; 1.0087x over previous
; #define PG8_STAGE(bufoff, gbase, voff) do { _Pragma("unroll") for (int _i = 0; _i < 2; ++_i) \
;         __builtin_amdgcn_global_load_lds((const unsigned*)((const char*)(gbase) + (voff)[_i]), (PG8_LAS unsigned*)(lds + (bufoff) + ldsw + _i * 8192), 16, 0, 0); } while (0)
; #define PG8_LDA(dst, b, h) do { _Pragma("unroll") for (int m = 0; m < 4; ++m) _Pragma("unroll") for (int k = 0; k < 2; ++k) dst[m][k] = *(const PG8_LAS bf16x8*)(lds + PG8_SA(b, h) + aoff + m * 2048 + k * 1024); } while (0)
; #define PG8_LDB(dst, b, h) do { _Pragma("unroll") for (int n = 0; n < 2; ++n) _Pragma("unroll") for (int k = 0; k < 2; ++k) dst[n][k] = *(const PG8_LAS bf16x8*)(lds + PG8_SB(b, h) + boff + n * 2048 + k * 1024); } while (0)
; #define PG8_MMA(ai, bj, At, Bt) do { __builtin_amdgcn_s_setprio(1); _Pragma("unroll") for (int m = 0; m < 4; ++m) _Pragma("unroll") for (int n = 0; n < 2; ++n) _Pragma("unroll") for (int k = 0; k < 2; ++k) \
;         acc[ai][bj][m][n] = __builtin_amdgcn_mfma_f32_16x16x32_bf16(Bt[n][k], At[m][k], acc[ai][bj][m][n], 0, 0, 0); __builtin_amdgcn_s_setprio(0); } while (0)
; #define PG8_WAIT_V(n) asm volatile("s_waitcnt vmcnt(" #n ")" ::: "memory")
; #define PG8_WAIT_L(n) asm volatile("s_waitcnt lgkmcnt(" #n ")" ::: "memory")
; #define PG8_BAR __builtin_amdgcn_s_barrier()
; #define PG8_SCHED __builtin_amdgcn_sched_barrier(0)
; template <class Epi, class Sched, bool ALIGN_EPI = false, bool SP2 = false>
; __device__ __forceinline__ void gemm_phase(PG8_LAS unsigned char* lds, const Gemm g, const Sched& S, const Epi& E, int tid_in) {
;     ...
;         for (int t = 0; t < nt; t += 2) {
;             const bool last = (t == nt - 2);
;             const char* a1 = cA + (size_t)(t + 1) * kstep;
;             const char* a2 = last ? nA : cA + (size_t)(t + 2) * kstep; const char* b2 = last ? nB : cB + (size_t)(t + 2) * kstep;
;             const char* a3 = a2 + kstep; const char* b3 = b2 + kstep;
;             if (last && has_next) S.a_ready(nxt);
;             if constexpr (SP2) {
;             PG8_LDB(B0, 0, 0); PG8_LDB(B1, 0, 1); PG8_SCHED; PG8_LDA(At, 0, 0); PG8_STAGE(PG8_SA(1, 1), a1 + hstep, voffA);
;             PG8_WAIT_V(8); PG8_WAIT_L(0); PG8_BAR; PG8_MMA(0, 0, At, B0); PG8_MMA(0, 1, At, B1); PG8_BAR; PG8_SCHED;
;             PG8_LDA(At, 0, 1); PG8_STAGE(PG8_SB(0, 0), b2, voffB); PG8_STAGE(PG8_SB(0, 1), b2 + hstep, voffB); PG8_STAGE(PG8_SA(0, 0), a2, voffA);
.LBB0_198:
	s_add_u32 s4, s2, 0xfffc0080
	s_addc_u32 s5, s3, -1
	s_add_i32 s43, 0, 0x10000
	s_cmp_eq_u32 s42, 12
	s_cselect_b32 s9, s0, s5
	s_cselect_b32 s8, s1, s4
	v_add_u32_e32 v80, s43, v237
	s_cselect_b32 s5, s38, s41
	s_cselect_b32 s4, s39, s40
	s_add_i32 s46, 0, 0x14000
	ds_read_b128 v[130:133], v80
	ds_read_b128 v[134:137], v80 offset:1024
	ds_read_b128 v[138:141], v80 offset:2048
	ds_read_b128 v[142:145], v80 offset:3072
	v_add_u32_e32 v80, s46, v237
	ds_read_b128 v[146:149], v80
	ds_read_b128 v[150:153], v80 offset:1024
	ds_read_b128 v[154:157], v80 offset:2048
	ds_read_b128 v[172:175], v80 offset:3072
	v_lshl_add_u64 v[158:159], s[2:3], 0, v[168:169]
	s_add_i32 m0, s17, 0xc000
	ds_read_b128 v[176:179], v238
	ds_read_b128 v[180:183], v238 offset:1024
	ds_read_b128 v[190:193], v238 offset:2048
	ds_read_b128 v[194:197], v238 offset:3072
	ds_read_b128 v[198:201], v238 offset:4096
	ds_read_b128 v[202:205], v238 offset:5120
	ds_read_b128 v[206:209], v238 offset:6144
	ds_read_b128 v[210:213], v238 offset:7168
	global_load_lds_dwordx4 v[158:159], off
	v_lshl_add_u64 v[158:159], s[2:3], 0, v[170:171]
	s_add_i32 m0, s17, 0xe000
	s_nop 0
	global_load_lds_dwordx4 v[158:159], off
	s_waitcnt vmcnt(8)
	s_waitcnt lgkmcnt(0)
	s_barrier
	s_setprio 1
	s_waitcnt lgkmcnt(0)
	v_mfma_f32_16x16x32_bf16 v[122:125], v[130:133], v[176:179], v[122:125]
	v_mfma_f32_16x16x32_bf16 v[126:129], v[138:141], v[176:179], v[126:129]
	v_mfma_f32_16x16x32_bf16 v[114:117], v[130:133], v[190:193], v[114:117]
	v_mfma_f32_16x16x32_bf16 v[118:121], v[138:141], v[190:193], v[118:121]
	v_mfma_f32_16x16x32_bf16 v[106:109], v[130:133], v[198:201], v[106:109]
	v_mfma_f32_16x16x32_bf16 v[110:113], v[138:141], v[198:201], v[110:113]
	v_mfma_f32_16x16x32_bf16 v[98:101], v[130:133], v[206:209], v[98:101]
	v_mfma_f32_16x16x32_bf16 v[102:105], v[138:141], v[206:209], v[102:105]
	v_mfma_f32_16x16x32_bf16 v[122:125], v[134:137], v[180:183], v[122:125]
	v_mfma_f32_16x16x32_bf16 v[126:129], v[142:145], v[180:183], v[126:129]
	v_mfma_f32_16x16x32_bf16 v[114:117], v[134:137], v[194:197], v[114:117]
	v_mfma_f32_16x16x32_bf16 v[118:121], v[142:145], v[194:197], v[118:121]
	v_mfma_f32_16x16x32_bf16 v[106:109], v[134:137], v[202:205], v[106:109]
	v_mfma_f32_16x16x32_bf16 v[110:113], v[142:145], v[202:205], v[110:113]
	v_mfma_f32_16x16x32_bf16 v[98:101], v[134:137], v[210:213], v[98:101]
	v_mfma_f32_16x16x32_bf16 v[102:105], v[142:145], v[210:213], v[102:105]
	v_mfma_f32_16x16x32_bf16 v[60:63], v[146:149], v[176:179], v[60:63]
	v_mfma_f32_16x16x32_bf16 v[56:59], v[154:157], v[176:179], v[56:59]
	v_mfma_f32_16x16x32_bf16 v[52:55], v[146:149], v[190:193], v[52:55]
	v_mfma_f32_16x16x32_bf16 v[48:51], v[154:157], v[190:193], v[48:51]
	v_mfma_f32_16x16x32_bf16 v[44:47], v[146:149], v[198:201], v[44:47]
	v_mfma_f32_16x16x32_bf16 v[40:43], v[154:157], v[198:201], v[40:43]
	v_mfma_f32_16x16x32_bf16 v[36:39], v[146:149], v[206:209], v[36:39]
	v_mfma_f32_16x16x32_bf16 v[32:35], v[154:157], v[206:209], v[32:35]
	v_mfma_f32_16x16x32_bf16 v[60:63], v[150:153], v[180:183], v[60:63]
	v_mfma_f32_16x16x32_bf16 v[56:59], v[172:175], v[180:183], v[56:59]
	v_mfma_f32_16x16x32_bf16 v[52:55], v[150:153], v[194:197], v[52:55]
	v_mfma_f32_16x16x32_bf16 v[48:51], v[172:175], v[194:197], v[48:51]
	v_mfma_f32_16x16x32_bf16 v[44:47], v[150:153], v[202:205], v[44:47]
	v_mfma_f32_16x16x32_bf16 v[40:43], v[172:175], v[202:205], v[40:43]
	v_mfma_f32_16x16x32_bf16 v[36:39], v[150:153], v[210:213], v[36:39]
	v_mfma_f32_16x16x32_bf16 v[32:35], v[172:175], v[210:213], v[32:35]
	s_setprio 0
	s_barrier
	s_add_i32 s43, s43, s14
	v_lshl_add_u64 v[158:159], s[4:5], 0, v[162:163]
	s_mov_b32 m0, s43
	ds_read_b128 v[176:179], v238 offset:16384
	ds_read_b128 v[180:183], v238 offset:17408
	ds_read_b128 v[190:193], v238 offset:18432
	ds_read_b128 v[194:197], v238 offset:19456
	ds_read_b128 v[198:201], v238 offset:20480
	ds_read_b128 v[202:205], v238 offset:21504
	ds_read_b128 v[206:209], v238 offset:22528
	ds_read_b128 v[210:213], v238 offset:23552
	global_load_lds_dwordx4 v[158:159], off
	s_add_i32 m0, s43, 0x2000
	s_add_u32 s44, s4, 0x40000
	v_lshl_add_u64 v[184:185], s[4:5], 0, v[166:167]
	s_addc_u32 s45, s5, 0
	s_add_i32 s43, s46, s14
	global_load_lds_dwordx4 v[184:185], off
	v_lshl_add_u64 v[186:187], s[44:45], 0, v[162:163]
	s_mov_b32 m0, s43
	v_lshl_add_u64 v[188:189], s[8:9], 0, v[164:165]
	global_load_lds_dwordx4 v[186:187], off
	v_lshl_add_u64 v[186:187], s[44:45], 0, v[166:167]
	s_add_i32 m0, s43, 0x2000
	s_nop 0
	global_load_lds_dwordx4 v[186:187], off
	v_lshl_add_u64 v[186:187], s[8:9], 0, v[160:161]
	s_mov_b32 m0, s17
	s_nop 0
	global_load_lds_dwordx4 v[186:187], off
	s_mov_b32 m0, s18
	s_nop 0
	global_load_lds_dwordx4 v[188:189], off
	s_waitcnt vmcnt(8)
	s_waitcnt lgkmcnt(0)
	s_barrier
; #define PG8_STAGE(bufoff, gbase, voff) do { _Pragma("unroll") for (int _i = 0; _i < 2; ++_i) \
;         __builtin_amdgcn_global_load_lds((const unsigned*)((const char*)(gbase) + (voff)[_i]), (PG8_LAS unsigned*)(lds + (bufoff) + ldsw + _i * 8192), 16, 0, 0); } while (0)
; #define PG8_LDA(dst, b, h) do { _Pragma("unroll") for (int m = 0; m < 4; ++m) _Pragma("unroll") for (int k = 0; k < 2; ++k) dst[m][k] = *(const PG8_LAS bf16x8*)(lds + PG8_SA(b, h) + aoff + m * 2048 + k * 1024); } while (0)
; #define PG8_LDB(dst, b, h) do { _Pragma("unroll") for (int n = 0; n < 2; ++n) _Pragma("unroll") for (int k = 0; k < 2; ++k) dst[n][k] = *(const PG8_LAS bf16x8*)(lds + PG8_SB(b, h) + boff + n * 2048 + k * 1024); } while (0)
; #define PG8_MMA(ai, bj, At, Bt) do { __builtin_amdgcn_s_setprio(1); _Pragma("unroll") for (int m = 0; m < 4; ++m) _Pragma("unroll") for (int n = 0; n < 2; ++n) _Pragma("unroll") for (int k = 0; k < 2; ++k) \
;         acc[ai][bj][m][n] = __builtin_amdgcn_mfma_f32_16x16x32_bf16(Bt[n][k], At[m][k], acc[ai][bj][m][n], 0, 0, 0); __builtin_amdgcn_s_setprio(0); } while (0)
; #define PG8_WAIT_V(n) asm volatile("s_waitcnt vmcnt(" #n ")" ::: "memory")
; #define PG8_WAIT_L(n) asm volatile("s_waitcnt lgkmcnt(" #n ")" ::: "memory")
; #define PG8_BAR __builtin_amdgcn_s_barrier()
; #define PG8_SCHED __builtin_amdgcn_sched_barrier(0)
; template <class Epi, class Sched, bool ALIGN_EPI = false, bool SP2 = false>
; __device__ __forceinline__ void gemm_phase(PG8_LAS unsigned char* lds, const Gemm g, const Sched& S, const Epi& E, int tid_in) {
;     ...
;             PG8_WAIT_V(8); PG8_WAIT_L(0); PG8_BAR; PG8_MMA(1, 0, At, B0); PG8_MMA(1, 1, At, B1); PG8_BAR; PG8_SCHED;
;             PG8_LDB(B0, 1, 0); PG8_LDB(B1, 1, 1); PG8_SCHED; PG8_LDA(At, 1, 0); PG8_STAGE(PG8_SA(0, 1), a2 + hstep, voffA);
;             PG8_WAIT_V(8); PG8_WAIT_L(0); PG8_BAR; PG8_MMA(0, 0, At, B0); PG8_MMA(0, 1, At, B1); PG8_BAR; PG8_SCHED;
	s_setprio 1
	s_waitcnt lgkmcnt(0)
	v_mfma_f32_16x16x32_bf16 v[90:93], v[130:133], v[176:179], v[90:93]
	v_mfma_f32_16x16x32_bf16 v[94:97], v[138:141], v[176:179], v[94:97]
	v_mfma_f32_16x16x32_bf16 v[82:85], v[130:133], v[190:193], v[82:85]
	v_mfma_f32_16x16x32_bf16 v[86:89], v[138:141], v[190:193], v[86:89]
	v_mfma_f32_16x16x32_bf16 v[72:75], v[130:133], v[198:201], v[72:75]
	v_mfma_f32_16x16x32_bf16 v[76:79], v[138:141], v[198:201], v[76:79]
	v_mfma_f32_16x16x32_bf16 v[64:67], v[130:133], v[206:209], v[64:67]
	v_mfma_f32_16x16x32_bf16 v[68:71], v[138:141], v[206:209], v[68:71]
	v_mfma_f32_16x16x32_bf16 v[90:93], v[134:137], v[180:183], v[90:93]
	v_mfma_f32_16x16x32_bf16 v[94:97], v[142:145], v[180:183], v[94:97]
	v_mfma_f32_16x16x32_bf16 v[82:85], v[134:137], v[194:197], v[82:85]
	v_mfma_f32_16x16x32_bf16 v[86:89], v[142:145], v[194:197], v[86:89]
	v_mfma_f32_16x16x32_bf16 v[72:75], v[134:137], v[202:205], v[72:75]
	v_mfma_f32_16x16x32_bf16 v[76:79], v[142:145], v[202:205], v[76:79]
	v_mfma_f32_16x16x32_bf16 v[64:67], v[134:137], v[210:213], v[64:67]
	v_mfma_f32_16x16x32_bf16 v[68:71], v[142:145], v[210:213], v[68:71]
	v_mfma_f32_16x16x32_bf16 v[28:31], v[146:149], v[176:179], v[28:31]
	v_mfma_f32_16x16x32_bf16 v[24:27], v[154:157], v[176:179], v[24:27]
	v_mfma_f32_16x16x32_bf16 v[20:23], v[146:149], v[190:193], v[20:23]
	v_mfma_f32_16x16x32_bf16 v[16:19], v[154:157], v[190:193], v[16:19]
	v_mfma_f32_16x16x32_bf16 v[12:15], v[146:149], v[198:201], v[12:15]
	v_mfma_f32_16x16x32_bf16 v[8:11], v[154:157], v[198:201], v[8:11]
	v_mfma_f32_16x16x32_bf16 v[4:7], v[146:149], v[206:209], v[4:7]
	v_mfma_f32_16x16x32_bf16 v[0:3], v[154:157], v[206:209], v[0:3]
	v_mfma_f32_16x16x32_bf16 v[28:31], v[150:153], v[180:183], v[28:31]
	v_mfma_f32_16x16x32_bf16 v[24:27], v[172:175], v[180:183], v[24:27]
	v_mfma_f32_16x16x32_bf16 v[20:23], v[150:153], v[194:197], v[20:23]
	v_mfma_f32_16x16x32_bf16 v[16:19], v[172:175], v[194:197], v[16:19]
	v_mfma_f32_16x16x32_bf16 v[12:15], v[150:153], v[202:205], v[12:15]
	v_mfma_f32_16x16x32_bf16 v[8:11], v[172:175], v[202:205], v[8:11]
	v_mfma_f32_16x16x32_bf16 v[4:7], v[150:153], v[210:213], v[4:7]
	v_mfma_f32_16x16x32_bf16 v[0:3], v[172:175], v[210:213], v[0:3]
	s_setprio 0
	s_barrier
	s_add_i32 s43, 0, 0x18000
	v_add_u32_e32 v80, s43, v237
	s_add_i32 s44, 0, 0x1c000
	ds_read_b128 v[130:133], v80
	ds_read_b128 v[134:137], v80 offset:1024
	ds_read_b128 v[138:141], v80 offset:2048
	ds_read_b128 v[142:145], v80 offset:3072
	v_add_u32_e32 v80, s44, v237
	ds_read_b128 v[146:149], v80
	ds_read_b128 v[150:153], v80 offset:1024
	ds_read_b128 v[154:157], v80 offset:2048
	ds_read_b128 v[172:175], v80 offset:3072
	s_add_u32 s8, s8, 0x40000
	s_addc_u32 s9, s9, 0
	s_mov_b32 m0, s19
	v_lshl_add_u64 v[214:215], s[8:9], 0, v[160:161]
	ds_read_b128 v[176:179], v238 offset:32768
	ds_read_b128 v[180:183], v238 offset:33792
	ds_read_b128 v[190:193], v238 offset:34816
	ds_read_b128 v[194:197], v238 offset:35840
	ds_read_b128 v[198:201], v238 offset:36864
	ds_read_b128 v[202:205], v238 offset:37888
	ds_read_b128 v[206:209], v238 offset:38912
	ds_read_b128 v[210:213], v238 offset:39936
	global_load_lds_dwordx4 v[214:215], off
	v_lshl_add_u64 v[214:215], s[8:9], 0, v[164:165]
	s_mov_b32 m0, s68
	s_nop 0
	global_load_lds_dwordx4 v[214:215], off
	s_waitcnt vmcnt(8)
	s_waitcnt lgkmcnt(0)
	s_barrier
	s_setprio 1
	s_waitcnt lgkmcnt(0)
	v_mfma_f32_16x16x32_bf16 v[122:125], v[130:133], v[176:179], v[122:125]
	v_mfma_f32_16x16x32_bf16 v[126:129], v[138:141], v[176:179], v[126:129]
	v_mfma_f32_16x16x32_bf16 v[114:117], v[130:133], v[190:193], v[114:117]
	v_mfma_f32_16x16x32_bf16 v[118:121], v[138:141], v[190:193], v[118:121]
	v_mfma_f32_16x16x32_bf16 v[106:109], v[130:133], v[198:201], v[106:109]
	v_mfma_f32_16x16x32_bf16 v[110:113], v[138:141], v[198:201], v[110:113]
	v_mfma_f32_16x16x32_bf16 v[98:101], v[130:133], v[206:209], v[98:101]
	v_mfma_f32_16x16x32_bf16 v[102:105], v[138:141], v[206:209], v[102:105]
	v_mfma_f32_16x16x32_bf16 v[122:125], v[134:137], v[180:183], v[122:125]
	v_mfma_f32_16x16x32_bf16 v[126:129], v[142:145], v[180:183], v[126:129]
	v_mfma_f32_16x16x32_bf16 v[114:117], v[134:137], v[194:197], v[114:117]
	v_mfma_f32_16x16x32_bf16 v[118:121], v[142:145], v[194:197], v[118:121]
	v_mfma_f32_16x16x32_bf16 v[106:109], v[134:137], v[202:205], v[106:109]
	v_mfma_f32_16x16x32_bf16 v[110:113], v[142:145], v[202:205], v[110:113]
	v_mfma_f32_16x16x32_bf16 v[98:101], v[134:137], v[210:213], v[98:101]
	v_mfma_f32_16x16x32_bf16 v[102:105], v[142:145], v[210:213], v[102:105]
	v_mfma_f32_16x16x32_bf16 v[60:63], v[146:149], v[176:179], v[60:63]
	v_mfma_f32_16x16x32_bf16 v[56:59], v[154:157], v[176:179], v[56:59]
	v_mfma_f32_16x16x32_bf16 v[52:55], v[146:149], v[190:193], v[52:55]
	v_mfma_f32_16x16x32_bf16 v[48:51], v[154:157], v[190:193], v[48:51]
	v_mfma_f32_16x16x32_bf16 v[44:47], v[146:149], v[198:201], v[44:47]
	v_mfma_f32_16x16x32_bf16 v[40:43], v[154:157], v[198:201], v[40:43]
	v_mfma_f32_16x16x32_bf16 v[36:39], v[146:149], v[206:209], v[36:39]
	v_mfma_f32_16x16x32_bf16 v[32:35], v[154:157], v[206:209], v[32:35]
	v_mfma_f32_16x16x32_bf16 v[60:63], v[150:153], v[180:183], v[60:63]
	v_mfma_f32_16x16x32_bf16 v[56:59], v[172:175], v[180:183], v[56:59]
	v_mfma_f32_16x16x32_bf16 v[52:55], v[150:153], v[194:197], v[52:55]
	v_mfma_f32_16x16x32_bf16 v[48:51], v[172:175], v[194:197], v[48:51]
	v_mfma_f32_16x16x32_bf16 v[44:47], v[150:153], v[202:205], v[44:47]
	v_mfma_f32_16x16x32_bf16 v[40:43], v[172:175], v[202:205], v[40:43]
	v_mfma_f32_16x16x32_bf16 v[36:39], v[150:153], v[210:213], v[36:39]
	v_mfma_f32_16x16x32_bf16 v[32:35], v[172:175], v[210:213], v[32:35]
	s_setprio 0
	s_barrier
; #define PG8_STAGE(bufoff, gbase, voff) do { _Pragma("unroll") for (int _i = 0; _i < 2; ++_i) \
;         __builtin_amdgcn_global_load_lds((const unsigned*)((const char*)(gbase) + (voff)[_i]), (PG8_LAS unsigned*)(lds + (bufoff) + ldsw + _i * 8192), 16, 0, 0); } while (0)
; #define PG8_LDA(dst, b, h) do { _Pragma("unroll") for (int m = 0; m < 4; ++m) _Pragma("unroll") for (int k = 0; k < 2; ++k) dst[m][k] = *(const PG8_LAS bf16x8*)(lds + PG8_SA(b, h) + aoff + m * 2048 + k * 1024); } while (0)
; #define PG8_MMA(ai, bj, At, Bt) do { __builtin_amdgcn_s_setprio(1); _Pragma("unroll") for (int m = 0; m < 4; ++m) _Pragma("unroll") for (int n = 0; n < 2; ++n) _Pragma("unroll") for (int k = 0; k < 2; ++k) \
;         acc[ai][bj][m][n] = __builtin_amdgcn_mfma_f32_16x16x32_bf16(Bt[n][k], At[m][k], acc[ai][bj][m][n], 0, 0, 0); __builtin_amdgcn_s_setprio(0); } while (0)
; #define PG8_WAIT_V(n) asm volatile("s_waitcnt vmcnt(" #n ")" ::: "memory")
; #define PG8_WAIT_L(n) asm volatile("s_waitcnt lgkmcnt(" #n ")" ::: "memory")
; #define PG8_BAR __builtin_amdgcn_s_barrier()
; #define PG8_SCHED __builtin_amdgcn_sched_barrier(0)
; template <class Epi, class Sched, bool ALIGN_EPI = false, bool SP2 = false>
; __device__ __forceinline__ void gemm_phase(PG8_LAS unsigned char* lds, const Gemm g, const Sched& S, const Epi& E, int tid_in) {
;     ...
;         for (int t = 0; t < nt; t += 2) {
;             const bool last = (t == nt - 2);
;             const char* a1 = cA + (size_t)(t + 1) * kstep;
;             const char* a2 = last ? nA : cA + (size_t)(t + 2) * kstep; const char* b2 = last ? nB : cB + (size_t)(t + 2) * kstep;
;     ...
;             PG8_LDA(At, 1, 1); PG8_STAGE(PG8_SB(1, 0), b3, voffB); PG8_STAGE(PG8_SB(1, 1), b3 + hstep, voffB); PG8_STAGE(PG8_SA(1, 0), a3, voffA);
;             PG8_WAIT_V(8); PG8_WAIT_L(0); PG8_BAR; PG8_MMA(1, 0, At, B0); PG8_MMA(1, 1, At, B1); PG8_BAR; PG8_SCHED;
	s_add_i32 s8, s43, s14
	v_lshl_add_u64 v[158:159], v[158:159], 0, s[6:7]
	s_mov_b32 m0, s8
	ds_read_b128 v[176:179], v238 offset:49152
	ds_read_b128 v[180:183], v238 offset:50176
	ds_read_b128 v[190:193], v238 offset:51200
	ds_read_b128 v[194:197], v238 offset:52224
	ds_read_b128 v[198:201], v238 offset:53248
	ds_read_b128 v[202:205], v238 offset:54272
	ds_read_b128 v[206:209], v238 offset:55296
	ds_read_b128 v[210:213], v238 offset:56320
	global_load_lds_dwordx4 v[158:159], off
	s_add_i32 m0, s8, 0x2000
	s_add_u32 s4, s4, 0x40080
	v_lshl_add_u64 v[158:159], v[184:185], 0, s[6:7]
	s_addc_u32 s5, s5, 0
	s_add_i32 s8, s44, s14
	global_load_lds_dwordx4 v[158:159], off
	v_lshl_add_u64 v[158:159], s[4:5], 0, v[162:163]
	s_mov_b32 m0, s8
	s_nop 0
	global_load_lds_dwordx4 v[158:159], off
	v_lshl_add_u64 v[158:159], s[4:5], 0, v[166:167]
	s_add_i32 m0, s8, 0x2000
	s_nop 0
	global_load_lds_dwordx4 v[158:159], off
	v_lshl_add_u64 v[158:159], v[186:187], 0, s[6:7]
	s_mov_b32 m0, s75
	s_nop 0
	global_load_lds_dwordx4 v[158:159], off
	v_lshl_add_u64 v[158:159], v[188:189], 0, s[6:7]
	s_mov_b32 m0, s76
	s_nop 0
	global_load_lds_dwordx4 v[158:159], off
	s_waitcnt vmcnt(8)
	s_waitcnt lgkmcnt(0)
	s_barrier
	s_setprio 1
	s_waitcnt lgkmcnt(0)
	v_mfma_f32_16x16x32_bf16 v[90:93], v[130:133], v[176:179], v[90:93]
	v_mfma_f32_16x16x32_bf16 v[94:97], v[138:141], v[176:179], v[94:97]
	v_mfma_f32_16x16x32_bf16 v[82:85], v[130:133], v[190:193], v[82:85]
	v_mfma_f32_16x16x32_bf16 v[86:89], v[138:141], v[190:193], v[86:89]
	v_mfma_f32_16x16x32_bf16 v[72:75], v[130:133], v[198:201], v[72:75]
	v_mfma_f32_16x16x32_bf16 v[76:79], v[138:141], v[198:201], v[76:79]
	v_mfma_f32_16x16x32_bf16 v[64:67], v[130:133], v[206:209], v[64:67]
	v_mfma_f32_16x16x32_bf16 v[68:71], v[138:141], v[206:209], v[68:71]
	v_mfma_f32_16x16x32_bf16 v[90:93], v[134:137], v[180:183], v[90:93]
	v_mfma_f32_16x16x32_bf16 v[94:97], v[142:145], v[180:183], v[94:97]
	v_mfma_f32_16x16x32_bf16 v[82:85], v[134:137], v[194:197], v[82:85]
	v_mfma_f32_16x16x32_bf16 v[86:89], v[142:145], v[194:197], v[86:89]
	v_mfma_f32_16x16x32_bf16 v[72:75], v[134:137], v[202:205], v[72:75]
	v_mfma_f32_16x16x32_bf16 v[76:79], v[142:145], v[202:205], v[76:79]
	v_mfma_f32_16x16x32_bf16 v[64:67], v[134:137], v[210:213], v[64:67]
	v_mfma_f32_16x16x32_bf16 v[68:71], v[142:145], v[210:213], v[68:71]
	v_mfma_f32_16x16x32_bf16 v[28:31], v[146:149], v[176:179], v[28:31]
	v_mfma_f32_16x16x32_bf16 v[24:27], v[154:157], v[176:179], v[24:27]
	v_mfma_f32_16x16x32_bf16 v[20:23], v[146:149], v[190:193], v[20:23]
	v_mfma_f32_16x16x32_bf16 v[16:19], v[154:157], v[190:193], v[16:19]
	v_mfma_f32_16x16x32_bf16 v[12:15], v[146:149], v[198:201], v[12:15]
	v_mfma_f32_16x16x32_bf16 v[8:11], v[154:157], v[198:201], v[8:11]
	v_mfma_f32_16x16x32_bf16 v[4:7], v[146:149], v[206:209], v[4:7]
	v_mfma_f32_16x16x32_bf16 v[0:3], v[154:157], v[206:209], v[0:3]
	v_mfma_f32_16x16x32_bf16 v[28:31], v[150:153], v[180:183], v[28:31]
	v_mfma_f32_16x16x32_bf16 v[24:27], v[172:175], v[180:183], v[24:27]
	v_mfma_f32_16x16x32_bf16 v[20:23], v[150:153], v[194:197], v[20:23]
	v_mfma_f32_16x16x32_bf16 v[16:19], v[172:175], v[194:197], v[16:19]
	v_mfma_f32_16x16x32_bf16 v[12:15], v[150:153], v[202:205], v[12:15]
	v_mfma_f32_16x16x32_bf16 v[8:11], v[172:175], v[202:205], v[8:11]
	v_mfma_f32_16x16x32_bf16 v[4:7], v[150:153], v[210:213], v[4:7]
	v_mfma_f32_16x16x32_bf16 v[0:3], v[172:175], v[210:213], v[0:3]
	s_setprio 0
	s_barrier
	s_add_i32 s42, s42, 2
	s_add_u32 s2, s2, 0x100
	s_addc_u32 s3, s3, 0
	s_add_u32 s40, s40, 0x100
	s_addc_u32 s41, s41, 0
	s_cmp_gt_u32 s42, 13
	s_cbranch_scc0 .LBB0_198
	s_and_b64 vcc, exec, s[64:65]
	s_mov_b32 s71, 0xfe03f81
	s_movk_i32 s73, 0x810
	s_cbranch_vccz .LBB0_201
	s_barrier

; #define PG8_STAGE(bufoff, gbase, voff) do { _Pragma("unroll") for (int _i = 0; _i < 2; ++_i) \
;         __builtin_amdgcn_global_load_lds((const unsigned*)((const char*)(gbase) + (voff)[_i]), (PG8_LAS unsigned*)(lds + (bufoff) + ldsw + _i * 8192), 16, 0, 0); } while (0)
; #define PG8_LDA(dst, b, h) do { _Pragma("unroll") for (int m = 0; m < 4; ++m) _Pragma("unroll") for (int k = 0; k < 2; ++k) dst[m][k] = *(const PG8_LAS bf16x8*)(lds + PG8_SA(b, h) + aoff + m * 2048 + k * 1024); } while (0)
; #define PG8_LDB(dst, b, h) do { _Pragma("unroll") for (int n = 0; n < 2; ++n) _Pragma("unroll") for (int k = 0; k < 2; ++k) dst[n][k] = *(const PG8_LAS bf16x8*)(lds + PG8_SB(b, h) + boff + n * 2048 + k * 1024); } while (0)
; #define PG8_MMA(ai, bj, At, Bt) do { __builtin_amdgcn_s_setprio(1); _Pragma("unroll") for (int m = 0; m < 4; ++m) _Pragma("unroll") for (int n = 0; n < 2; ++n) _Pragma("unroll") for (int k = 0; k < 2; ++k) \
;         acc[ai][bj][m][n] = __builtin_amdgcn_mfma_f32_16x16x32_bf16(Bt[n][k], At[m][k], acc[ai][bj][m][n], 0, 0, 0); __builtin_amdgcn_s_setprio(0); } while (0)
; #define PG8_WAIT_V(n) asm volatile("s_waitcnt vmcnt(" #n ")" ::: "memory")
; #define PG8_BAR __builtin_amdgcn_s_barrier()
; template <class Epi, class Sched, bool ALIGN_EPI = false, bool SP2 = false>
; __device__ __forceinline__ void gemm_phase(PG8_LAS unsigned char* lds, const Gemm g, const Sched& S, const Epi& E, int tid_in) {
;     ...
;         for (int t = 0; t < nt; t += 2) {
;             const bool last = (t == nt - 2);
;             const char* a1 = cA + (size_t)(t + 1) * kstep;
;             const char* a2 = last ? nA : cA + (size_t)(t + 2) * kstep; const char* b2 = last ? nB : cB + (size_t)(t + 2) * kstep;
;             const char* a3 = a2 + kstep; const char* b3 = b2 + kstep;
;             if (last && has_next) S.a_ready(nxt);
;             if constexpr (SP2) {
;             PG8_LDB(B0, 0, 0); PG8_LDB(B1, 0, 1); PG8_SCHED; PG8_LDA(At, 0, 0); PG8_STAGE(PG8_SA(1, 1), a1 + hstep, voffA);
;             PG8_WAIT_V(8); PG8_WAIT_L(0); PG8_BAR; PG8_MMA(0, 0, At, B0); PG8_MMA(0, 1, At, B1); PG8_BAR; PG8_SCHED;
;             PG8_LDA(At, 0, 1); PG8_STAGE(PG8_SB(0, 0), b2, voffB); PG8_STAGE(PG8_SB(0, 1), b2 + hstep, voffB); PG8_STAGE(PG8_SA(0, 0), a2, voffA);
;             PG8_WAIT_V(8); PG8_WAIT_L(0); PG8_BAR; PG8_MMA(1, 0, At, B0); PG8_MMA(1, 1, At, B1); PG8_BAR; PG8_SCHED;
.LBB0_1305:
	s_add_u32 s50, s48, 0xfffe0080
	s_addc_u32 s51, s49, -1
	s_add_i32 s64, 0, 0x10000
	s_cmp_eq_u32 s63, 4
	s_cselect_b32 s53, s0, s51
	s_cselect_b32 s52, s1, s50
	s_cselect_b32 s51, s39, s62
	s_cselect_b32 s50, s41, s61
	s_add_i32 s66, 0, 0x14000
	v_add_u32_e32 v142, s64, v172
	v_add_u32_e32 v168, s66, v172
	ds_read_b128 v[130:133], v142
	ds_read_b128 v[134:137], v142 offset:1024
	ds_read_b128 v[138:141], v142 offset:2048
	ds_read_b128 v[142:145], v142 offset:3072
	ds_read_b128 v[146:149], v168
	ds_read_b128 v[160:163], v168 offset:1024
	ds_read_b128 v[164:167], v168 offset:2048
	ds_read_b128 v[174:177], v168 offset:3072
	v_lshl_add_u64 v[168:169], s[48:49], 0, v[156:157]
	s_add_i32 m0, s16, 0xc000
	ds_read_b128 v[178:181], v173
	ds_read_b128 v[182:185], v173 offset:1024
	ds_read_b128 v[190:193], v173 offset:2048
	ds_read_b128 v[194:197], v173 offset:3072
	ds_read_b128 v[198:201], v173 offset:4096
	ds_read_b128 v[202:205], v173 offset:5120
	ds_read_b128 v[206:209], v173 offset:6144
	ds_read_b128 v[210:213], v173 offset:7168
	global_load_lds_dwordx4 v[168:169], off
	v_lshl_add_u64 v[168:169], s[48:49], 0, v[158:159]
	s_add_i32 m0, s16, 0xe000
	s_nop 0
	global_load_lds_dwordx4 v[168:169], off
	s_waitcnt vmcnt(8)
	s_waitcnt lgkmcnt(0)
	s_barrier
	s_setprio 1
	s_waitcnt lgkmcnt(0)
	v_mfma_f32_16x16x32_bf16 v[126:129], v[130:133], v[178:181], v[126:129]
	v_mfma_f32_16x16x32_bf16 v[122:125], v[138:141], v[178:181], v[122:125]
	v_mfma_f32_16x16x32_bf16 v[110:113], v[130:133], v[190:193], v[110:113]
	v_mfma_f32_16x16x32_bf16 v[106:109], v[138:141], v[190:193], v[106:109]
	v_mfma_f32_16x16x32_bf16 v[98:101], v[130:133], v[198:201], v[98:101]
	v_mfma_f32_16x16x32_bf16 v[90:93], v[138:141], v[198:201], v[90:93]
	v_mfma_f32_16x16x32_bf16 v[82:85], v[130:133], v[206:209], v[82:85]
	v_mfma_f32_16x16x32_bf16 v[72:75], v[138:141], v[206:209], v[72:75]
	v_mfma_f32_16x16x32_bf16 v[126:129], v[134:137], v[182:185], v[126:129]
	v_mfma_f32_16x16x32_bf16 v[122:125], v[142:145], v[182:185], v[122:125]
	v_mfma_f32_16x16x32_bf16 v[110:113], v[134:137], v[194:197], v[110:113]
	v_mfma_f32_16x16x32_bf16 v[106:109], v[142:145], v[194:197], v[106:109]
	v_mfma_f32_16x16x32_bf16 v[98:101], v[134:137], v[202:205], v[98:101]
	v_mfma_f32_16x16x32_bf16 v[90:93], v[142:145], v[202:205], v[90:93]
	v_mfma_f32_16x16x32_bf16 v[82:85], v[134:137], v[210:213], v[82:85]
	v_mfma_f32_16x16x32_bf16 v[72:75], v[142:145], v[210:213], v[72:75]
	v_mfma_f32_16x16x32_bf16 v[118:121], v[146:149], v[178:181], v[118:121]
	v_mfma_f32_16x16x32_bf16 v[114:117], v[164:167], v[178:181], v[114:117]
	v_mfma_f32_16x16x32_bf16 v[102:105], v[146:149], v[190:193], v[102:105]
	v_mfma_f32_16x16x32_bf16 v[94:97], v[164:167], v[190:193], v[94:97]
	v_mfma_f32_16x16x32_bf16 v[86:89], v[146:149], v[198:201], v[86:89]
	v_mfma_f32_16x16x32_bf16 v[76:79], v[164:167], v[198:201], v[76:79]
	v_mfma_f32_16x16x32_bf16 v[68:71], v[146:149], v[206:209], v[68:71]
	v_mfma_f32_16x16x32_bf16 v[64:67], v[164:167], v[206:209], v[64:67]
	v_mfma_f32_16x16x32_bf16 v[118:121], v[160:163], v[182:185], v[118:121]
	v_mfma_f32_16x16x32_bf16 v[114:117], v[174:177], v[182:185], v[114:117]
	v_mfma_f32_16x16x32_bf16 v[102:105], v[160:163], v[194:197], v[102:105]
	v_mfma_f32_16x16x32_bf16 v[94:97], v[174:177], v[194:197], v[94:97]
	v_mfma_f32_16x16x32_bf16 v[86:89], v[160:163], v[202:205], v[86:89]
	v_mfma_f32_16x16x32_bf16 v[76:79], v[174:177], v[202:205], v[76:79]
	v_mfma_f32_16x16x32_bf16 v[68:71], v[160:163], v[210:213], v[68:71]
	v_mfma_f32_16x16x32_bf16 v[64:67], v[174:177], v[210:213], v[64:67]
	s_setprio 0
	s_barrier
	s_add_i32 s64, s64, s15
	v_lshl_add_u64 v[168:169], s[50:51], 0, v[80:81]
	s_mov_b32 m0, s64
	ds_read_b128 v[178:181], v173 offset:16384
	ds_read_b128 v[182:185], v173 offset:17408
	ds_read_b128 v[190:193], v173 offset:18432
	ds_read_b128 v[194:197], v173 offset:19456
	ds_read_b128 v[198:201], v173 offset:20480
	ds_read_b128 v[202:205], v173 offset:21504
	ds_read_b128 v[206:209], v173 offset:22528
	ds_read_b128 v[210:213], v173 offset:23552
	global_load_lds_dwordx4 v[168:169], off
	s_add_i32 m0, s64, 0x2000
	s_add_u32 s64, s50, 0x20000
	v_lshl_add_u64 v[186:187], s[50:51], 0, v[154:155]
	s_addc_u32 s65, s51, 0
	s_add_i32 s66, s66, s15
	global_load_lds_dwordx4 v[186:187], off
	v_lshl_add_u64 v[188:189], s[64:65], 0, v[80:81]
	s_mov_b32 m0, s66
	v_lshl_add_u64 v[214:215], s[52:53], 0, v[152:153]
	global_load_lds_dwordx4 v[188:189], off
	v_lshl_add_u64 v[188:189], s[64:65], 0, v[154:155]
	s_add_i32 m0, s66, 0x2000
	s_nop 0
	global_load_lds_dwordx4 v[188:189], off
	v_lshl_add_u64 v[188:189], s[52:53], 0, v[150:151]
	s_mov_b32 m0, s16
	s_nop 0
	global_load_lds_dwordx4 v[188:189], off
	s_mov_b32 m0, s17
	s_nop 0
	global_load_lds_dwordx4 v[214:215], off
	s_waitcnt vmcnt(8)
	s_waitcnt lgkmcnt(0)
	s_barrier
; #define PG8_STAGE(bufoff, gbase, voff) do { _Pragma("unroll") for (int _i = 0; _i < 2; ++_i) \
;         __builtin_amdgcn_global_load_lds((const unsigned*)((const char*)(gbase) + (voff)[_i]), (PG8_LAS unsigned*)(lds + (bufoff) + ldsw + _i * 8192), 16, 0, 0); } while (0)
; #define PG8_LDA(dst, b, h) do { _Pragma("unroll") for (int m = 0; m < 4; ++m) _Pragma("unroll") for (int k = 0; k < 2; ++k) dst[m][k] = *(const PG8_LAS bf16x8*)(lds + PG8_SA(b, h) + aoff + m * 2048 + k * 1024); } while (0)
; #define PG8_LDB(dst, b, h) do { _Pragma("unroll") for (int n = 0; n < 2; ++n) _Pragma("unroll") for (int k = 0; k < 2; ++k) dst[n][k] = *(const PG8_LAS bf16x8*)(lds + PG8_SB(b, h) + boff + n * 2048 + k * 1024); } while (0)
; #define PG8_MMA(ai, bj, At, Bt) do { __builtin_amdgcn_s_setprio(1); _Pragma("unroll") for (int m = 0; m < 4; ++m) _Pragma("unroll") for (int n = 0; n < 2; ++n) _Pragma("unroll") for (int k = 0; k < 2; ++k) \
;         acc[ai][bj][m][n] = __builtin_amdgcn_mfma_f32_16x16x32_bf16(Bt[n][k], At[m][k], acc[ai][bj][m][n], 0, 0, 0); __builtin_amdgcn_s_setprio(0); } while (0)
; #define PG8_WAIT_V(n) asm volatile("s_waitcnt vmcnt(" #n ")" ::: "memory")
; #define PG8_WAIT_L(n) asm volatile("s_waitcnt lgkmcnt(" #n ")" ::: "memory")
; #define PG8_BAR __builtin_amdgcn_s_barrier()
; #define PG8_SCHED __builtin_amdgcn_sched_barrier(0)
; template <class Epi, class Sched, bool ALIGN_EPI = false, bool SP2 = false>
; __device__ __forceinline__ void gemm_phase(PG8_LAS unsigned char* lds, const Gemm g, const Sched& S, const Epi& E, int tid_in) {
;     ...
;             PG8_WAIT_V(8); PG8_WAIT_L(0); PG8_BAR; PG8_MMA(1, 0, At, B0); PG8_MMA(1, 1, At, B1); PG8_BAR; PG8_SCHED;
;             PG8_LDB(B0, 1, 0); PG8_LDB(B1, 1, 1); PG8_SCHED; PG8_LDA(At, 1, 0); PG8_STAGE(PG8_SA(0, 1), a2 + hstep, voffA);
;             PG8_WAIT_V(8); PG8_WAIT_L(0); PG8_BAR; PG8_MMA(0, 0, At, B0); PG8_MMA(0, 1, At, B1); PG8_BAR; PG8_SCHED;
	s_setprio 1
	s_waitcnt lgkmcnt(0)
	v_mfma_f32_16x16x32_bf16 v[60:63], v[130:133], v[178:181], v[60:63]
	v_mfma_f32_16x16x32_bf16 v[56:59], v[138:141], v[178:181], v[56:59]
	v_mfma_f32_16x16x32_bf16 v[48:51], v[130:133], v[190:193], v[48:51]
	v_mfma_f32_16x16x32_bf16 v[40:43], v[138:141], v[190:193], v[40:43]
	v_mfma_f32_16x16x32_bf16 v[32:35], v[130:133], v[198:201], v[32:35]
	v_mfma_f32_16x16x32_bf16 v[24:27], v[138:141], v[198:201], v[24:27]
	v_mfma_f32_16x16x32_bf16 v[16:19], v[130:133], v[206:209], v[16:19]
	v_mfma_f32_16x16x32_bf16 v[8:11], v[138:141], v[206:209], v[8:11]
	v_mfma_f32_16x16x32_bf16 v[60:63], v[134:137], v[182:185], v[60:63]
	v_mfma_f32_16x16x32_bf16 v[56:59], v[142:145], v[182:185], v[56:59]
	v_mfma_f32_16x16x32_bf16 v[48:51], v[134:137], v[194:197], v[48:51]
	v_mfma_f32_16x16x32_bf16 v[40:43], v[142:145], v[194:197], v[40:43]
	v_mfma_f32_16x16x32_bf16 v[32:35], v[134:137], v[202:205], v[32:35]
	v_mfma_f32_16x16x32_bf16 v[24:27], v[142:145], v[202:205], v[24:27]
	v_mfma_f32_16x16x32_bf16 v[16:19], v[134:137], v[210:213], v[16:19]
	v_mfma_f32_16x16x32_bf16 v[8:11], v[142:145], v[210:213], v[8:11]
	v_mfma_f32_16x16x32_bf16 v[52:55], v[146:149], v[178:181], v[52:55]
	v_mfma_f32_16x16x32_bf16 v[44:47], v[164:167], v[178:181], v[44:47]
	v_mfma_f32_16x16x32_bf16 v[36:39], v[146:149], v[190:193], v[36:39]
	v_mfma_f32_16x16x32_bf16 v[28:31], v[164:167], v[190:193], v[28:31]
	v_mfma_f32_16x16x32_bf16 v[20:23], v[146:149], v[198:201], v[20:23]
	v_mfma_f32_16x16x32_bf16 v[12:15], v[164:167], v[198:201], v[12:15]
	v_mfma_f32_16x16x32_bf16 v[4:7], v[146:149], v[206:209], v[4:7]
	v_mfma_f32_16x16x32_bf16 v[0:3], v[164:167], v[206:209], v[0:3]
	v_mfma_f32_16x16x32_bf16 v[52:55], v[160:163], v[182:185], v[52:55]
	v_mfma_f32_16x16x32_bf16 v[44:47], v[174:177], v[182:185], v[44:47]
	v_mfma_f32_16x16x32_bf16 v[36:39], v[160:163], v[194:197], v[36:39]
	v_mfma_f32_16x16x32_bf16 v[28:31], v[174:177], v[194:197], v[28:31]
	v_mfma_f32_16x16x32_bf16 v[20:23], v[160:163], v[202:205], v[20:23]
	v_mfma_f32_16x16x32_bf16 v[12:15], v[174:177], v[202:205], v[12:15]
	v_mfma_f32_16x16x32_bf16 v[4:7], v[160:163], v[210:213], v[4:7]
	v_mfma_f32_16x16x32_bf16 v[0:3], v[174:177], v[210:213], v[0:3]
	s_setprio 0
	s_barrier
	s_add_i32 s64, 0, 0x18000
	s_add_i32 s65, 0, 0x1c000
	v_add_u32_e32 v142, s64, v172
	v_add_u32_e32 v174, s65, v172
	ds_read_b128 v[130:133], v142
	ds_read_b128 v[134:137], v142 offset:1024
	ds_read_b128 v[138:141], v142 offset:2048
	ds_read_b128 v[142:145], v142 offset:3072
	ds_read_b128 v[146:149], v174
	ds_read_b128 v[160:163], v174 offset:1024
	ds_read_b128 v[164:167], v174 offset:2048
	ds_read_b128 v[174:177], v174 offset:3072
	s_add_u32 s52, s52, 0x20000
	s_addc_u32 s53, s53, 0
	s_mov_b32 m0, s18
	v_lshl_add_u64 v[226:227], s[52:53], 0, v[150:151]
	ds_read_b128 v[178:181], v173 offset:32768
	ds_read_b128 v[182:185], v173 offset:33792
	ds_read_b128 v[190:193], v173 offset:34816
	ds_read_b128 v[194:197], v173 offset:35840
	ds_read_b128 v[198:201], v173 offset:36864
	ds_read_b128 v[202:205], v173 offset:37888
	ds_read_b128 v[206:209], v173 offset:38912
	ds_read_b128 v[210:213], v173 offset:39936
	global_load_lds_dwordx4 v[226:227], off
	v_lshl_add_u64 v[226:227], s[52:53], 0, v[152:153]
	s_mov_b32 m0, s19
	s_nop 0
	global_load_lds_dwordx4 v[226:227], off
	s_waitcnt vmcnt(8)
	s_waitcnt lgkmcnt(0)
	s_barrier
	s_setprio 1
	s_waitcnt lgkmcnt(0)
	v_mfma_f32_16x16x32_bf16 v[126:129], v[130:133], v[178:181], v[126:129]
	v_mfma_f32_16x16x32_bf16 v[122:125], v[138:141], v[178:181], v[122:125]
	v_mfma_f32_16x16x32_bf16 v[110:113], v[130:133], v[190:193], v[110:113]
	v_mfma_f32_16x16x32_bf16 v[106:109], v[138:141], v[190:193], v[106:109]
	v_mfma_f32_16x16x32_bf16 v[98:101], v[130:133], v[198:201], v[98:101]
	v_mfma_f32_16x16x32_bf16 v[90:93], v[138:141], v[198:201], v[90:93]
	v_mfma_f32_16x16x32_bf16 v[82:85], v[130:133], v[206:209], v[82:85]
	v_mfma_f32_16x16x32_bf16 v[72:75], v[138:141], v[206:209], v[72:75]
	v_mfma_f32_16x16x32_bf16 v[126:129], v[134:137], v[182:185], v[126:129]
	v_mfma_f32_16x16x32_bf16 v[122:125], v[142:145], v[182:185], v[122:125]
	v_mfma_f32_16x16x32_bf16 v[110:113], v[134:137], v[194:197], v[110:113]
	v_mfma_f32_16x16x32_bf16 v[106:109], v[142:145], v[194:197], v[106:109]
	v_mfma_f32_16x16x32_bf16 v[98:101], v[134:137], v[202:205], v[98:101]
	v_mfma_f32_16x16x32_bf16 v[90:93], v[142:145], v[202:205], v[90:93]
	v_mfma_f32_16x16x32_bf16 v[82:85], v[134:137], v[210:213], v[82:85]
	v_mfma_f32_16x16x32_bf16 v[72:75], v[142:145], v[210:213], v[72:75]
	v_mfma_f32_16x16x32_bf16 v[118:121], v[146:149], v[178:181], v[118:121]
	v_mfma_f32_16x16x32_bf16 v[114:117], v[164:167], v[178:181], v[114:117]
	v_mfma_f32_16x16x32_bf16 v[102:105], v[146:149], v[190:193], v[102:105]
	v_mfma_f32_16x16x32_bf16 v[94:97], v[164:167], v[190:193], v[94:97]
	v_mfma_f32_16x16x32_bf16 v[86:89], v[146:149], v[198:201], v[86:89]
	v_mfma_f32_16x16x32_bf16 v[76:79], v[164:167], v[198:201], v[76:79]
	v_mfma_f32_16x16x32_bf16 v[68:71], v[146:149], v[206:209], v[68:71]
	v_mfma_f32_16x16x32_bf16 v[64:67], v[164:167], v[206:209], v[64:67]
	v_mfma_f32_16x16x32_bf16 v[118:121], v[160:163], v[182:185], v[118:121]
	v_mfma_f32_16x16x32_bf16 v[114:117], v[174:177], v[182:185], v[114:117]
	v_mfma_f32_16x16x32_bf16 v[102:105], v[160:163], v[194:197], v[102:105]
	v_mfma_f32_16x16x32_bf16 v[94:97], v[174:177], v[194:197], v[94:97]
	v_mfma_f32_16x16x32_bf16 v[86:89], v[160:163], v[202:205], v[86:89]
	v_mfma_f32_16x16x32_bf16 v[76:79], v[174:177], v[202:205], v[76:79]
	v_mfma_f32_16x16x32_bf16 v[68:71], v[160:163], v[210:213], v[68:71]
	v_mfma_f32_16x16x32_bf16 v[64:67], v[174:177], v[210:213], v[64:67]
	s_setprio 0
	s_barrier
; #define PG8_STAGE(bufoff, gbase, voff) do { _Pragma("unroll") for (int _i = 0; _i < 2; ++_i) \
;         __builtin_amdgcn_global_load_lds((const unsigned*)((const char*)(gbase) + (voff)[_i]), (PG8_LAS unsigned*)(lds + (bufoff) + ldsw + _i * 8192), 16, 0, 0); } while (0)
; #define PG8_LDA(dst, b, h) do { _Pragma("unroll") for (int m = 0; m < 4; ++m) _Pragma("unroll") for (int k = 0; k < 2; ++k) dst[m][k] = *(const PG8_LAS bf16x8*)(lds + PG8_SA(b, h) + aoff + m * 2048 + k * 1024); } while (0)
; #define PG8_MMA(ai, bj, At, Bt) do { __builtin_amdgcn_s_setprio(1); _Pragma("unroll") for (int m = 0; m < 4; ++m) _Pragma("unroll") for (int n = 0; n < 2; ++n) _Pragma("unroll") for (int k = 0; k < 2; ++k) \
;         acc[ai][bj][m][n] = __builtin_amdgcn_mfma_f32_16x16x32_bf16(Bt[n][k], At[m][k], acc[ai][bj][m][n], 0, 0, 0); __builtin_amdgcn_s_setprio(0); } while (0)
; #define PG8_WAIT_V(n) asm volatile("s_waitcnt vmcnt(" #n ")" ::: "memory")
; #define PG8_WAIT_L(n) asm volatile("s_waitcnt lgkmcnt(" #n ")" ::: "memory")
; #define PG8_BAR __builtin_amdgcn_s_barrier()
; #define PG8_SCHED __builtin_amdgcn_sched_barrier(0)
; template <class Epi, class Sched, bool ALIGN_EPI = false, bool SP2 = false>
; __device__ __forceinline__ void gemm_phase(PG8_LAS unsigned char* lds, const Gemm g, const Sched& S, const Epi& E, int tid_in) {
;     ...
;         for (int t = 0; t < nt; t += 2) {
;             const bool last = (t == nt - 2);
;             const char* a1 = cA + (size_t)(t + 1) * kstep;
;             const char* a2 = last ? nA : cA + (size_t)(t + 2) * kstep; const char* b2 = last ? nB : cB + (size_t)(t + 2) * kstep;
;     ...
;             PG8_LDA(At, 1, 1); PG8_STAGE(PG8_SB(1, 0), b3, voffB); PG8_STAGE(PG8_SB(1, 1), b3 + hstep, voffB); PG8_STAGE(PG8_SA(1, 0), a3, voffA);
;             PG8_WAIT_V(8); PG8_WAIT_L(0); PG8_BAR; PG8_MMA(1, 0, At, B0); PG8_MMA(1, 1, At, B1); PG8_BAR; PG8_SCHED;
	s_add_i32 s52, s64, s15
	v_lshl_add_u64 v[168:169], v[168:169], 0, s[6:7]
	s_mov_b32 m0, s52
	ds_read_b128 v[178:181], v173 offset:49152
	ds_read_b128 v[182:185], v173 offset:50176
	ds_read_b128 v[190:193], v173 offset:51200
	ds_read_b128 v[194:197], v173 offset:52224
	ds_read_b128 v[198:201], v173 offset:53248
	ds_read_b128 v[202:205], v173 offset:54272
	ds_read_b128 v[206:209], v173 offset:55296
	ds_read_b128 v[210:213], v173 offset:56320
	global_load_lds_dwordx4 v[168:169], off
	s_add_i32 m0, s52, 0x2000
	s_add_u32 s50, s50, 0x20080
	v_lshl_add_u64 v[168:169], v[186:187], 0, s[6:7]
	s_addc_u32 s51, s51, 0
	s_add_i32 s52, s65, s15
	global_load_lds_dwordx4 v[168:169], off
	v_lshl_add_u64 v[168:169], s[50:51], 0, v[80:81]
	s_mov_b32 m0, s52
	s_nop 0
	global_load_lds_dwordx4 v[168:169], off
	v_lshl_add_u64 v[168:169], s[50:51], 0, v[154:155]
	s_add_i32 m0, s52, 0x2000
	s_nop 0
	global_load_lds_dwordx4 v[168:169], off
	v_lshl_add_u64 v[168:169], v[188:189], 0, s[6:7]
	s_mov_b32 m0, s54
	s_nop 0
	global_load_lds_dwordx4 v[168:169], off
	v_lshl_add_u64 v[168:169], v[214:215], 0, s[6:7]
	s_mov_b32 m0, s55
	s_nop 0
	global_load_lds_dwordx4 v[168:169], off
	s_waitcnt vmcnt(8)
	s_waitcnt lgkmcnt(0)
	s_barrier
	s_setprio 1
	s_waitcnt lgkmcnt(0)
	v_mfma_f32_16x16x32_bf16 v[60:63], v[130:133], v[178:181], v[60:63]
	v_mfma_f32_16x16x32_bf16 v[56:59], v[138:141], v[178:181], v[56:59]
	v_mfma_f32_16x16x32_bf16 v[48:51], v[130:133], v[190:193], v[48:51]
	v_mfma_f32_16x16x32_bf16 v[40:43], v[138:141], v[190:193], v[40:43]
	v_mfma_f32_16x16x32_bf16 v[32:35], v[130:133], v[198:201], v[32:35]
	v_mfma_f32_16x16x32_bf16 v[24:27], v[138:141], v[198:201], v[24:27]
	v_mfma_f32_16x16x32_bf16 v[16:19], v[130:133], v[206:209], v[16:19]
	v_mfma_f32_16x16x32_bf16 v[8:11], v[138:141], v[206:209], v[8:11]
	v_mfma_f32_16x16x32_bf16 v[60:63], v[134:137], v[182:185], v[60:63]
	v_mfma_f32_16x16x32_bf16 v[56:59], v[142:145], v[182:185], v[56:59]
	v_mfma_f32_16x16x32_bf16 v[48:51], v[134:137], v[194:197], v[48:51]
	v_mfma_f32_16x16x32_bf16 v[40:43], v[142:145], v[194:197], v[40:43]
	v_mfma_f32_16x16x32_bf16 v[32:35], v[134:137], v[202:205], v[32:35]
	v_mfma_f32_16x16x32_bf16 v[24:27], v[142:145], v[202:205], v[24:27]
	v_mfma_f32_16x16x32_bf16 v[16:19], v[134:137], v[210:213], v[16:19]
	v_mfma_f32_16x16x32_bf16 v[8:11], v[142:145], v[210:213], v[8:11]
	v_mfma_f32_16x16x32_bf16 v[52:55], v[146:149], v[178:181], v[52:55]
	v_mfma_f32_16x16x32_bf16 v[44:47], v[164:167], v[178:181], v[44:47]
	v_mfma_f32_16x16x32_bf16 v[36:39], v[146:149], v[190:193], v[36:39]
	v_mfma_f32_16x16x32_bf16 v[28:31], v[164:167], v[190:193], v[28:31]
	v_mfma_f32_16x16x32_bf16 v[20:23], v[146:149], v[198:201], v[20:23]
	v_mfma_f32_16x16x32_bf16 v[12:15], v[164:167], v[198:201], v[12:15]
	v_mfma_f32_16x16x32_bf16 v[4:7], v[146:149], v[206:209], v[4:7]
	v_mfma_f32_16x16x32_bf16 v[0:3], v[164:167], v[206:209], v[0:3]
	v_mfma_f32_16x16x32_bf16 v[52:55], v[160:163], v[182:185], v[52:55]
	v_mfma_f32_16x16x32_bf16 v[44:47], v[174:177], v[182:185], v[44:47]
	v_mfma_f32_16x16x32_bf16 v[36:39], v[160:163], v[194:197], v[36:39]
	v_mfma_f32_16x16x32_bf16 v[28:31], v[174:177], v[194:197], v[28:31]
	v_mfma_f32_16x16x32_bf16 v[20:23], v[160:163], v[202:205], v[20:23]
	v_mfma_f32_16x16x32_bf16 v[12:15], v[174:177], v[202:205], v[12:15]
	v_mfma_f32_16x16x32_bf16 v[4:7], v[160:163], v[210:213], v[4:7]
	v_mfma_f32_16x16x32_bf16 v[0:3], v[174:177], v[210:213], v[0:3]
	s_setprio 0
	s_barrier
	s_add_i32 s63, s63, 2
	s_add_u32 s48, s48, 0x100
	s_addc_u32 s49, s49, 0
	s_add_u32 s61, s61, 0x100
	s_addc_u32 s62, s62, 0
	s_cmp_gt_u32 s63, 5
	s_cbranch_scc0 .LBB0_1305
	s_and_b64 vcc, exec, s[8:9]
	s_cbranch_vccz .LBB0_1308
	s_barrier

; #define PG8_STAGE(bufoff, gbase, voff) do { _Pragma("unroll") for (int _i = 0; _i < 2; ++_i) \
;         __builtin_amdgcn_global_load_lds((const unsigned*)((const char*)(gbase) + (voff)[_i]), (PG8_LAS unsigned*)(lds + (bufoff) + ldsw + _i * 8192), 16, 0, 0); } while (0)
; #define PG8_LDA(dst, b, h) do { _Pragma("unroll") for (int m = 0; m < 4; ++m) _Pragma("unroll") for (int k = 0; k < 2; ++k) dst[m][k] = *(const PG8_LAS bf16x8*)(lds + PG8_SA(b, h) + aoff + m * 2048 + k * 1024); } while (0)
; #define PG8_LDB(dst, b, h) do { _Pragma("unroll") for (int n = 0; n < 2; ++n) _Pragma("unroll") for (int k = 0; k < 2; ++k) dst[n][k] = *(const PG8_LAS bf16x8*)(lds + PG8_SB(b, h) + boff + n * 2048 + k * 1024); } while (0)
; #define PG8_MMA(ai, bj, At, Bt) do { __builtin_amdgcn_s_setprio(1); _Pragma("unroll") for (int m = 0; m < 4; ++m) _Pragma("unroll") for (int n = 0; n < 2; ++n) _Pragma("unroll") for (int k = 0; k < 2; ++k) \
;         acc[ai][bj][m][n] = __builtin_amdgcn_mfma_f32_16x16x32_bf16(Bt[n][k], At[m][k], acc[ai][bj][m][n], 0, 0, 0); __builtin_amdgcn_s_setprio(0); } while (0)
; #define PG8_WAIT_V(n) asm volatile("s_waitcnt vmcnt(" #n ")" ::: "memory")
; #define PG8_BAR __builtin_amdgcn_s_barrier()
; template <class Epi, class Sched, bool ALIGN_EPI = false, bool SP2 = false>
; __device__ __forceinline__ void gemm_phase(PG8_LAS unsigned char* lds, const Gemm g, const Sched& S, const Epi& E, int tid_in) {
;     ...
;         for (int t = 0; t < nt; t += 2) {
;             const bool last = (t == nt - 2);
;             const char* a1 = cA + (size_t)(t + 1) * kstep;
;             const char* a2 = last ? nA : cA + (size_t)(t + 2) * kstep; const char* b2 = last ? nB : cB + (size_t)(t + 2) * kstep;
;             const char* a3 = a2 + kstep; const char* b3 = b2 + kstep;
;             if (last && has_next) S.a_ready(nxt);
;             if constexpr (SP2) {
;             PG8_LDB(B0, 0, 0); PG8_LDB(B1, 0, 1); PG8_SCHED; PG8_LDA(At, 0, 0); PG8_STAGE(PG8_SA(1, 1), a1 + hstep, voffA);
;             PG8_WAIT_V(8); PG8_WAIT_L(0); PG8_BAR; PG8_MMA(0, 0, At, B0); PG8_MMA(0, 1, At, B1); PG8_BAR; PG8_SCHED;
;             PG8_LDA(At, 0, 1); PG8_STAGE(PG8_SB(0, 0), b2, voffB); PG8_STAGE(PG8_SB(0, 1), b2 + hstep, voffB); PG8_STAGE(PG8_SA(0, 0), a2, voffA);
;             PG8_WAIT_V(8); PG8_WAIT_L(0); PG8_BAR; PG8_MMA(1, 0, At, B0); PG8_MMA(1, 1, At, B1); PG8_BAR; PG8_SCHED;
.LBB0_1340:
	s_add_u32 s54, s52, 0xfffc0080
	s_addc_u32 s55, s53, -1
	s_add_i32 s66, 0, 0x10000
	s_cmp_eq_u32 s65, 12
	s_cselect_b32 s57, s0, s55
	s_cselect_b32 s56, s1, s54
	s_cselect_b32 s55, s41, s64
	s_cselect_b32 s54, s45, s63
	s_add_i32 s68, 0, 0x14000
	v_add_u32_e32 v142, s66, v214
	v_add_u32_e32 v158, s68, v214
	ds_read_b128 v[130:133], v142
	ds_read_b128 v[134:137], v142 offset:1024
	ds_read_b128 v[138:141], v142 offset:2048
	ds_read_b128 v[142:145], v142 offset:3072
	ds_read_b128 v[146:149], v158
	ds_read_b128 v[150:153], v158 offset:1024
	ds_read_b128 v[154:157], v158 offset:2048
	ds_read_b128 v[158:161], v158 offset:3072
	v_lshl_add_u64 v[186:187], s[52:53], 0, v[196:197]
	s_add_i32 m0, s16, 0xc000
	ds_read_b128 v[162:165], v215
	ds_read_b128 v[166:169], v215 offset:1024
	ds_read_b128 v[170:173], v215 offset:2048
	ds_read_b128 v[174:177], v215 offset:3072
	ds_read_b128 v[178:181], v215 offset:4096
	ds_read_b128 v[182:185], v215 offset:5120
	ds_read_b128 v[200:203], v215 offset:6144
	ds_read_b128 v[204:207], v215 offset:7168
	global_load_lds_dwordx4 v[186:187], off
	v_lshl_add_u64 v[186:187], s[52:53], 0, v[198:199]
	s_add_i32 m0, s16, 0xe000
	s_nop 0
	global_load_lds_dwordx4 v[186:187], off
	s_waitcnt vmcnt(8)
	s_waitcnt lgkmcnt(0)
	s_barrier
	s_setprio 1
	s_waitcnt lgkmcnt(0)
	v_mfma_f32_16x16x32_bf16 v[126:129], v[130:133], v[162:165], v[126:129]
	v_mfma_f32_16x16x32_bf16 v[122:125], v[138:141], v[162:165], v[122:125]
	v_mfma_f32_16x16x32_bf16 v[110:113], v[130:133], v[170:173], v[110:113]
	v_mfma_f32_16x16x32_bf16 v[106:109], v[138:141], v[170:173], v[106:109]
	v_mfma_f32_16x16x32_bf16 v[94:97], v[130:133], v[178:181], v[94:97]
	v_mfma_f32_16x16x32_bf16 v[90:93], v[138:141], v[178:181], v[90:93]
	v_mfma_f32_16x16x32_bf16 v[76:79], v[130:133], v[200:203], v[76:79]
	v_mfma_f32_16x16x32_bf16 v[72:75], v[138:141], v[200:203], v[72:75]
	v_mfma_f32_16x16x32_bf16 v[126:129], v[134:137], v[166:169], v[126:129]
	v_mfma_f32_16x16x32_bf16 v[122:125], v[142:145], v[166:169], v[122:125]
	v_mfma_f32_16x16x32_bf16 v[110:113], v[134:137], v[174:177], v[110:113]
	v_mfma_f32_16x16x32_bf16 v[106:109], v[142:145], v[174:177], v[106:109]
	v_mfma_f32_16x16x32_bf16 v[94:97], v[134:137], v[182:185], v[94:97]
	v_mfma_f32_16x16x32_bf16 v[90:93], v[142:145], v[182:185], v[90:93]
	v_mfma_f32_16x16x32_bf16 v[76:79], v[134:137], v[204:207], v[76:79]
	v_mfma_f32_16x16x32_bf16 v[72:75], v[142:145], v[204:207], v[72:75]
	v_mfma_f32_16x16x32_bf16 v[118:121], v[146:149], v[162:165], v[118:121]
	v_mfma_f32_16x16x32_bf16 v[114:117], v[154:157], v[162:165], v[114:117]
	v_mfma_f32_16x16x32_bf16 v[102:105], v[146:149], v[170:173], v[102:105]
	v_mfma_f32_16x16x32_bf16 v[98:101], v[154:157], v[170:173], v[98:101]
	v_mfma_f32_16x16x32_bf16 v[86:89], v[146:149], v[178:181], v[86:89]
	v_mfma_f32_16x16x32_bf16 v[82:85], v[154:157], v[178:181], v[82:85]
	v_mfma_f32_16x16x32_bf16 v[68:71], v[146:149], v[200:203], v[68:71]
	v_mfma_f32_16x16x32_bf16 v[64:67], v[154:157], v[200:203], v[64:67]
	v_mfma_f32_16x16x32_bf16 v[118:121], v[150:153], v[166:169], v[118:121]
	v_mfma_f32_16x16x32_bf16 v[114:117], v[158:161], v[166:169], v[114:117]
	v_mfma_f32_16x16x32_bf16 v[102:105], v[150:153], v[174:177], v[102:105]
	v_mfma_f32_16x16x32_bf16 v[98:101], v[158:161], v[174:177], v[98:101]
	v_mfma_f32_16x16x32_bf16 v[86:89], v[150:153], v[182:185], v[86:89]
	v_mfma_f32_16x16x32_bf16 v[82:85], v[158:161], v[182:185], v[82:85]
	v_mfma_f32_16x16x32_bf16 v[68:71], v[150:153], v[204:207], v[68:71]
	v_mfma_f32_16x16x32_bf16 v[64:67], v[158:161], v[204:207], v[64:67]
	s_setprio 0
	s_barrier
	s_add_i32 s66, s66, s15
	v_lshl_add_u64 v[186:187], s[54:55], 0, v[80:81]
	s_mov_b32 m0, s66
	ds_read_b128 v[162:165], v215 offset:16384
	ds_read_b128 v[166:169], v215 offset:17408
	ds_read_b128 v[170:173], v215 offset:18432
	ds_read_b128 v[174:177], v215 offset:19456
	ds_read_b128 v[178:181], v215 offset:20480
	ds_read_b128 v[182:185], v215 offset:21504
	ds_read_b128 v[200:203], v215 offset:22528
	ds_read_b128 v[204:207], v215 offset:23552
	global_load_lds_dwordx4 v[186:187], off
	s_add_i32 m0, s66, 0x2000
	s_add_u32 s66, s54, 0x40000
	v_lshl_add_u64 v[188:189], s[54:55], 0, v[194:195]
	s_addc_u32 s67, s55, 0
	s_add_i32 s68, s68, s15
	global_load_lds_dwordx4 v[188:189], off
	v_lshl_add_u64 v[208:209], s[66:67], 0, v[80:81]
	s_mov_b32 m0, s68
	v_lshl_add_u64 v[210:211], s[56:57], 0, v[192:193]
	global_load_lds_dwordx4 v[208:209], off
	v_lshl_add_u64 v[208:209], s[66:67], 0, v[194:195]
	s_add_i32 m0, s68, 0x2000
	s_nop 0
	global_load_lds_dwordx4 v[208:209], off
	v_lshl_add_u64 v[208:209], s[56:57], 0, v[190:191]
	s_mov_b32 m0, s16
	s_nop 0
	global_load_lds_dwordx4 v[208:209], off
	s_mov_b32 m0, s17
	s_nop 0
	global_load_lds_dwordx4 v[210:211], off
	s_waitcnt vmcnt(8)
	s_waitcnt lgkmcnt(0)
	s_barrier
; #define PG8_STAGE(bufoff, gbase, voff) do { _Pragma("unroll") for (int _i = 0; _i < 2; ++_i) \
;         __builtin_amdgcn_global_load_lds((const unsigned*)((const char*)(gbase) + (voff)[_i]), (PG8_LAS unsigned*)(lds + (bufoff) + ldsw + _i * 8192), 16, 0, 0); } while (0)
; #define PG8_LDA(dst, b, h) do { _Pragma("unroll") for (int m = 0; m < 4; ++m) _Pragma("unroll") for (int k = 0; k < 2; ++k) dst[m][k] = *(const PG8_LAS bf16x8*)(lds + PG8_SA(b, h) + aoff + m * 2048 + k * 1024); } while (0)
; #define PG8_LDB(dst, b, h) do { _Pragma("unroll") for (int n = 0; n < 2; ++n) _Pragma("unroll") for (int k = 0; k < 2; ++k) dst[n][k] = *(const PG8_LAS bf16x8*)(lds + PG8_SB(b, h) + boff + n * 2048 + k * 1024); } while (0)
; #define PG8_MMA(ai, bj, At, Bt) do { __builtin_amdgcn_s_setprio(1); _Pragma("unroll") for (int m = 0; m < 4; ++m) _Pragma("unroll") for (int n = 0; n < 2; ++n) _Pragma("unroll") for (int k = 0; k < 2; ++k) \
;         acc[ai][bj][m][n] = __builtin_amdgcn_mfma_f32_16x16x32_bf16(Bt[n][k], At[m][k], acc[ai][bj][m][n], 0, 0, 0); __builtin_amdgcn_s_setprio(0); } while (0)
; #define PG8_WAIT_V(n) asm volatile("s_waitcnt vmcnt(" #n ")" ::: "memory")
; #define PG8_WAIT_L(n) asm volatile("s_waitcnt lgkmcnt(" #n ")" ::: "memory")
; #define PG8_BAR __builtin_amdgcn_s_barrier()
; #define PG8_SCHED __builtin_amdgcn_sched_barrier(0)
; template <class Epi, class Sched, bool ALIGN_EPI = false, bool SP2 = false>
; __device__ __forceinline__ void gemm_phase(PG8_LAS unsigned char* lds, const Gemm g, const Sched& S, const Epi& E, int tid_in) {
;     ...
;             PG8_WAIT_V(8); PG8_WAIT_L(0); PG8_BAR; PG8_MMA(1, 0, At, B0); PG8_MMA(1, 1, At, B1); PG8_BAR; PG8_SCHED;
;             PG8_LDB(B0, 1, 0); PG8_LDB(B1, 1, 1); PG8_SCHED; PG8_LDA(At, 1, 0); PG8_STAGE(PG8_SA(0, 1), a2 + hstep, voffA);
;             PG8_WAIT_V(8); PG8_WAIT_L(0); PG8_BAR; PG8_MMA(0, 0, At, B0); PG8_MMA(0, 1, At, B1); PG8_BAR; PG8_SCHED;
	s_setprio 1
	s_waitcnt lgkmcnt(0)
	v_mfma_f32_16x16x32_bf16 v[60:63], v[130:133], v[162:165], v[60:63]
	v_mfma_f32_16x16x32_bf16 v[56:59], v[138:141], v[162:165], v[56:59]
	v_mfma_f32_16x16x32_bf16 v[44:47], v[130:133], v[170:173], v[44:47]
	v_mfma_f32_16x16x32_bf16 v[40:43], v[138:141], v[170:173], v[40:43]
	v_mfma_f32_16x16x32_bf16 v[28:31], v[130:133], v[178:181], v[28:31]
	v_mfma_f32_16x16x32_bf16 v[24:27], v[138:141], v[178:181], v[24:27]
	v_mfma_f32_16x16x32_bf16 v[12:15], v[130:133], v[200:203], v[12:15]
	v_mfma_f32_16x16x32_bf16 v[8:11], v[138:141], v[200:203], v[8:11]
	v_mfma_f32_16x16x32_bf16 v[60:63], v[134:137], v[166:169], v[60:63]
	v_mfma_f32_16x16x32_bf16 v[56:59], v[142:145], v[166:169], v[56:59]
	v_mfma_f32_16x16x32_bf16 v[44:47], v[134:137], v[174:177], v[44:47]
	v_mfma_f32_16x16x32_bf16 v[40:43], v[142:145], v[174:177], v[40:43]
	v_mfma_f32_16x16x32_bf16 v[28:31], v[134:137], v[182:185], v[28:31]
	v_mfma_f32_16x16x32_bf16 v[24:27], v[142:145], v[182:185], v[24:27]
	v_mfma_f32_16x16x32_bf16 v[12:15], v[134:137], v[204:207], v[12:15]
	v_mfma_f32_16x16x32_bf16 v[8:11], v[142:145], v[204:207], v[8:11]
	v_mfma_f32_16x16x32_bf16 v[52:55], v[146:149], v[162:165], v[52:55]
	v_mfma_f32_16x16x32_bf16 v[48:51], v[154:157], v[162:165], v[48:51]
	v_mfma_f32_16x16x32_bf16 v[36:39], v[146:149], v[170:173], v[36:39]
	v_mfma_f32_16x16x32_bf16 v[32:35], v[154:157], v[170:173], v[32:35]
	v_mfma_f32_16x16x32_bf16 v[20:23], v[146:149], v[178:181], v[20:23]
	v_mfma_f32_16x16x32_bf16 v[16:19], v[154:157], v[178:181], v[16:19]
	v_mfma_f32_16x16x32_bf16 v[4:7], v[146:149], v[200:203], v[4:7]
	v_mfma_f32_16x16x32_bf16 v[0:3], v[154:157], v[200:203], v[0:3]
	v_mfma_f32_16x16x32_bf16 v[52:55], v[150:153], v[166:169], v[52:55]
	v_mfma_f32_16x16x32_bf16 v[48:51], v[158:161], v[166:169], v[48:51]
	v_mfma_f32_16x16x32_bf16 v[36:39], v[150:153], v[174:177], v[36:39]
	v_mfma_f32_16x16x32_bf16 v[32:35], v[158:161], v[174:177], v[32:35]
	v_mfma_f32_16x16x32_bf16 v[20:23], v[150:153], v[182:185], v[20:23]
	v_mfma_f32_16x16x32_bf16 v[16:19], v[158:161], v[182:185], v[16:19]
	v_mfma_f32_16x16x32_bf16 v[4:7], v[150:153], v[204:207], v[4:7]
	v_mfma_f32_16x16x32_bf16 v[0:3], v[158:161], v[204:207], v[0:3]
	s_setprio 0
	s_barrier
	s_add_i32 s66, 0, 0x18000
	s_add_i32 s67, 0, 0x1c000
	v_add_u32_e32 v142, s66, v214
	v_add_u32_e32 v158, s67, v214
	ds_read_b128 v[130:133], v142
	ds_read_b128 v[134:137], v142 offset:1024
	ds_read_b128 v[138:141], v142 offset:2048
	ds_read_b128 v[142:145], v142 offset:3072
	ds_read_b128 v[146:149], v158
	ds_read_b128 v[150:153], v158 offset:1024
	ds_read_b128 v[154:157], v158 offset:2048
	ds_read_b128 v[158:161], v158 offset:3072
	s_add_u32 s56, s56, 0x40000
	s_addc_u32 s57, s57, 0
	s_mov_b32 m0, s18
	v_lshl_add_u64 v[226:227], s[56:57], 0, v[190:191]
	ds_read_b128 v[162:165], v215 offset:32768
	ds_read_b128 v[166:169], v215 offset:33792
	ds_read_b128 v[170:173], v215 offset:34816
	ds_read_b128 v[174:177], v215 offset:35840
	ds_read_b128 v[178:181], v215 offset:36864
	ds_read_b128 v[182:185], v215 offset:37888
	ds_read_b128 v[200:203], v215 offset:38912
	ds_read_b128 v[204:207], v215 offset:39936
	global_load_lds_dwordx4 v[226:227], off
	v_lshl_add_u64 v[226:227], s[56:57], 0, v[192:193]
	s_mov_b32 m0, s19
	s_nop 0
	global_load_lds_dwordx4 v[226:227], off
	s_waitcnt vmcnt(8)
	s_waitcnt lgkmcnt(0)
	s_barrier
	s_setprio 1
	s_waitcnt lgkmcnt(0)
	v_mfma_f32_16x16x32_bf16 v[126:129], v[130:133], v[162:165], v[126:129]
	v_mfma_f32_16x16x32_bf16 v[122:125], v[138:141], v[162:165], v[122:125]
	v_mfma_f32_16x16x32_bf16 v[110:113], v[130:133], v[170:173], v[110:113]
	v_mfma_f32_16x16x32_bf16 v[106:109], v[138:141], v[170:173], v[106:109]
	v_mfma_f32_16x16x32_bf16 v[94:97], v[130:133], v[178:181], v[94:97]
	v_mfma_f32_16x16x32_bf16 v[90:93], v[138:141], v[178:181], v[90:93]
	v_mfma_f32_16x16x32_bf16 v[76:79], v[130:133], v[200:203], v[76:79]
	v_mfma_f32_16x16x32_bf16 v[72:75], v[138:141], v[200:203], v[72:75]
	v_mfma_f32_16x16x32_bf16 v[126:129], v[134:137], v[166:169], v[126:129]
	v_mfma_f32_16x16x32_bf16 v[122:125], v[142:145], v[166:169], v[122:125]
	v_mfma_f32_16x16x32_bf16 v[110:113], v[134:137], v[174:177], v[110:113]
	v_mfma_f32_16x16x32_bf16 v[106:109], v[142:145], v[174:177], v[106:109]
	v_mfma_f32_16x16x32_bf16 v[94:97], v[134:137], v[182:185], v[94:97]
	v_mfma_f32_16x16x32_bf16 v[90:93], v[142:145], v[182:185], v[90:93]
	v_mfma_f32_16x16x32_bf16 v[76:79], v[134:137], v[204:207], v[76:79]
	v_mfma_f32_16x16x32_bf16 v[72:75], v[142:145], v[204:207], v[72:75]
	v_mfma_f32_16x16x32_bf16 v[118:121], v[146:149], v[162:165], v[118:121]
	v_mfma_f32_16x16x32_bf16 v[114:117], v[154:157], v[162:165], v[114:117]
	v_mfma_f32_16x16x32_bf16 v[102:105], v[146:149], v[170:173], v[102:105]
	v_mfma_f32_16x16x32_bf16 v[98:101], v[154:157], v[170:173], v[98:101]
	v_mfma_f32_16x16x32_bf16 v[86:89], v[146:149], v[178:181], v[86:89]
	v_mfma_f32_16x16x32_bf16 v[82:85], v[154:157], v[178:181], v[82:85]
	v_mfma_f32_16x16x32_bf16 v[68:71], v[146:149], v[200:203], v[68:71]
	v_mfma_f32_16x16x32_bf16 v[64:67], v[154:157], v[200:203], v[64:67]
	v_mfma_f32_16x16x32_bf16 v[118:121], v[150:153], v[166:169], v[118:121]
	v_mfma_f32_16x16x32_bf16 v[114:117], v[158:161], v[166:169], v[114:117]
	v_mfma_f32_16x16x32_bf16 v[102:105], v[150:153], v[174:177], v[102:105]
	v_mfma_f32_16x16x32_bf16 v[98:101], v[158:161], v[174:177], v[98:101]
	v_mfma_f32_16x16x32_bf16 v[86:89], v[150:153], v[182:185], v[86:89]
	v_mfma_f32_16x16x32_bf16 v[82:85], v[158:161], v[182:185], v[82:85]
	v_mfma_f32_16x16x32_bf16 v[68:71], v[150:153], v[204:207], v[68:71]
	v_mfma_f32_16x16x32_bf16 v[64:67], v[158:161], v[204:207], v[64:67]
	s_setprio 0
	s_barrier
; #define PG8_STAGE(bufoff, gbase, voff) do { _Pragma("unroll") for (int _i = 0; _i < 2; ++_i) \
;         __builtin_amdgcn_global_load_lds((const unsigned*)((const char*)(gbase) + (voff)[_i]), (PG8_LAS unsigned*)(lds + (bufoff) + ldsw + _i * 8192), 16, 0, 0); } while (0)
; #define PG8_LDA(dst, b, h) do { _Pragma("unroll") for (int m = 0; m < 4; ++m) _Pragma("unroll") for (int k = 0; k < 2; ++k) dst[m][k] = *(const PG8_LAS bf16x8*)(lds + PG8_SA(b, h) + aoff + m * 2048 + k * 1024); } while (0)
; #define PG8_MMA(ai, bj, At, Bt) do { __builtin_amdgcn_s_setprio(1); _Pragma("unroll") for (int m = 0; m < 4; ++m) _Pragma("unroll") for (int n = 0; n < 2; ++n) _Pragma("unroll") for (int k = 0; k < 2; ++k) \
;         acc[ai][bj][m][n] = __builtin_amdgcn_mfma_f32_16x16x32_bf16(Bt[n][k], At[m][k], acc[ai][bj][m][n], 0, 0, 0); __builtin_amdgcn_s_setprio(0); } while (0)
; #define PG8_WAIT_V(n) asm volatile("s_waitcnt vmcnt(" #n ")" ::: "memory")
; #define PG8_WAIT_L(n) asm volatile("s_waitcnt lgkmcnt(" #n ")" ::: "memory")
; #define PG8_BAR __builtin_amdgcn_s_barrier()
; #define PG8_SCHED __builtin_amdgcn_sched_barrier(0)
; template <class Epi, class Sched, bool ALIGN_EPI = false, bool SP2 = false>
; __device__ __forceinline__ void gemm_phase(PG8_LAS unsigned char* lds, const Gemm g, const Sched& S, const Epi& E, int tid_in) {
;     ...
;         for (int t = 0; t < nt; t += 2) {
;             const bool last = (t == nt - 2);
;             const char* a1 = cA + (size_t)(t + 1) * kstep;
;             const char* a2 = last ? nA : cA + (size_t)(t + 2) * kstep; const char* b2 = last ? nB : cB + (size_t)(t + 2) * kstep;
;     ...
;             PG8_LDA(At, 1, 1); PG8_STAGE(PG8_SB(1, 0), b3, voffB); PG8_STAGE(PG8_SB(1, 1), b3 + hstep, voffB); PG8_STAGE(PG8_SA(1, 0), a3, voffA);
;             PG8_WAIT_V(8); PG8_WAIT_L(0); PG8_BAR; PG8_MMA(1, 0, At, B0); PG8_MMA(1, 1, At, B1); PG8_BAR; PG8_SCHED;
	s_add_i32 s56, s66, s15
	v_lshl_add_u64 v[186:187], v[186:187], 0, s[6:7]
	s_mov_b32 m0, s56
	ds_read_b128 v[162:165], v215 offset:49152
	ds_read_b128 v[166:169], v215 offset:50176
	ds_read_b128 v[170:173], v215 offset:51200
	ds_read_b128 v[174:177], v215 offset:52224
	ds_read_b128 v[178:181], v215 offset:53248
	ds_read_b128 v[182:185], v215 offset:54272
	ds_read_b128 v[200:203], v215 offset:55296
	ds_read_b128 v[204:207], v215 offset:56320
	global_load_lds_dwordx4 v[186:187], off
	s_add_i32 m0, s56, 0x2000
	s_add_u32 s54, s54, 0x40080
	v_lshl_add_u64 v[186:187], v[188:189], 0, s[6:7]
	s_addc_u32 s55, s55, 0
	s_add_i32 s56, s67, s15
	global_load_lds_dwordx4 v[186:187], off
	v_lshl_add_u64 v[186:187], s[54:55], 0, v[80:81]
	s_mov_b32 m0, s56
	s_nop 0
	global_load_lds_dwordx4 v[186:187], off
	v_lshl_add_u64 v[186:187], s[54:55], 0, v[194:195]
	s_add_i32 m0, s56, 0x2000
	s_nop 0
	global_load_lds_dwordx4 v[186:187], off
	v_lshl_add_u64 v[186:187], v[208:209], 0, s[6:7]
	s_mov_b32 m0, s58
	s_nop 0
	global_load_lds_dwordx4 v[186:187], off
	v_lshl_add_u64 v[186:187], v[210:211], 0, s[6:7]
	s_mov_b32 m0, s59
	s_nop 0
	global_load_lds_dwordx4 v[186:187], off
	s_waitcnt vmcnt(8)
	s_waitcnt lgkmcnt(0)
	s_barrier
	s_setprio 1
	s_waitcnt lgkmcnt(0)
	v_mfma_f32_16x16x32_bf16 v[60:63], v[130:133], v[162:165], v[60:63]
	v_mfma_f32_16x16x32_bf16 v[56:59], v[138:141], v[162:165], v[56:59]
	v_mfma_f32_16x16x32_bf16 v[44:47], v[130:133], v[170:173], v[44:47]
	v_mfma_f32_16x16x32_bf16 v[40:43], v[138:141], v[170:173], v[40:43]
	v_mfma_f32_16x16x32_bf16 v[28:31], v[130:133], v[178:181], v[28:31]
	v_mfma_f32_16x16x32_bf16 v[24:27], v[138:141], v[178:181], v[24:27]
	v_mfma_f32_16x16x32_bf16 v[12:15], v[130:133], v[200:203], v[12:15]
	v_mfma_f32_16x16x32_bf16 v[8:11], v[138:141], v[200:203], v[8:11]
	v_mfma_f32_16x16x32_bf16 v[60:63], v[134:137], v[166:169], v[60:63]
	v_mfma_f32_16x16x32_bf16 v[56:59], v[142:145], v[166:169], v[56:59]
	v_mfma_f32_16x16x32_bf16 v[44:47], v[134:137], v[174:177], v[44:47]
	v_mfma_f32_16x16x32_bf16 v[40:43], v[142:145], v[174:177], v[40:43]
	v_mfma_f32_16x16x32_bf16 v[28:31], v[134:137], v[182:185], v[28:31]
	v_mfma_f32_16x16x32_bf16 v[24:27], v[142:145], v[182:185], v[24:27]
	v_mfma_f32_16x16x32_bf16 v[12:15], v[134:137], v[204:207], v[12:15]
	v_mfma_f32_16x16x32_bf16 v[8:11], v[142:145], v[204:207], v[8:11]
	v_mfma_f32_16x16x32_bf16 v[52:55], v[146:149], v[162:165], v[52:55]
	v_mfma_f32_16x16x32_bf16 v[48:51], v[154:157], v[162:165], v[48:51]
	v_mfma_f32_16x16x32_bf16 v[36:39], v[146:149], v[170:173], v[36:39]
	v_mfma_f32_16x16x32_bf16 v[32:35], v[154:157], v[170:173], v[32:35]
	v_mfma_f32_16x16x32_bf16 v[20:23], v[146:149], v[178:181], v[20:23]
	v_mfma_f32_16x16x32_bf16 v[16:19], v[154:157], v[178:181], v[16:19]
	v_mfma_f32_16x16x32_bf16 v[4:7], v[146:149], v[200:203], v[4:7]
	v_mfma_f32_16x16x32_bf16 v[0:3], v[154:157], v[200:203], v[0:3]
	v_mfma_f32_16x16x32_bf16 v[52:55], v[150:153], v[166:169], v[52:55]
	v_mfma_f32_16x16x32_bf16 v[48:51], v[158:161], v[166:169], v[48:51]
	v_mfma_f32_16x16x32_bf16 v[36:39], v[150:153], v[174:177], v[36:39]
	v_mfma_f32_16x16x32_bf16 v[32:35], v[158:161], v[174:177], v[32:35]
	v_mfma_f32_16x16x32_bf16 v[20:23], v[150:153], v[182:185], v[20:23]
	v_mfma_f32_16x16x32_bf16 v[16:19], v[158:161], v[182:185], v[16:19]
	v_mfma_f32_16x16x32_bf16 v[4:7], v[150:153], v[204:207], v[4:7]
	v_mfma_f32_16x16x32_bf16 v[0:3], v[158:161], v[204:207], v[0:3]
	s_setprio 0
	s_barrier
	s_add_i32 s65, s65, 2
	s_add_u32 s52, s52, 0x100
	s_addc_u32 s53, s53, 0
	s_add_u32 s63, s63, 0x100
	s_addc_u32 s64, s64, 0
	s_cmp_gt_u32 s65, 13
	s_cbranch_scc0 .LBB0_1340
	s_and_b64 vcc, exec, s[8:9]
	s_cbranch_vccz .LBB0_1343
	s_barrier

; #define PG8_STAGE(bufoff, gbase, voff) do { _Pragma("unroll") for (int _i = 0; _i < 2; ++_i) \
;         __builtin_amdgcn_global_load_lds((const unsigned*)((const char*)(gbase) + (voff)[_i]), (PG8_LAS unsigned*)(lds + (bufoff) + ldsw + _i * 8192), 16, 0, 0); } while (0)
; #define PG8_LDA(dst, b, h) do { _Pragma("unroll") for (int m = 0; m < 4; ++m) _Pragma("unroll") for (int k = 0; k < 2; ++k) dst[m][k] = *(const PG8_LAS bf16x8*)(lds + PG8_SA(b, h) + aoff + m * 2048 + k * 1024); } while (0)
; #define PG8_LDB(dst, b, h) do { _Pragma("unroll") for (int n = 0; n < 2; ++n) _Pragma("unroll") for (int k = 0; k < 2; ++k) dst[n][k] = *(const PG8_LAS bf16x8*)(lds + PG8_SB(b, h) + boff + n * 2048 + k * 1024); } while (0)
; #define PG8_MMA(ai, bj, At, Bt) do { __builtin_amdgcn_s_setprio(1); _Pragma("unroll") for (int m = 0; m < 4; ++m) _Pragma("unroll") for (int n = 0; n < 2; ++n) _Pragma("unroll") for (int k = 0; k < 2; ++k) \
;         acc[ai][bj][m][n] = __builtin_amdgcn_mfma_f32_16x16x32_bf16(Bt[n][k], At[m][k], acc[ai][bj][m][n], 0, 0, 0); __builtin_amdgcn_s_setprio(0); } while (0)
; #define PG8_WAIT_V(n) asm volatile("s_waitcnt vmcnt(" #n ")" ::: "memory")
; #define PG8_BAR __builtin_amdgcn_s_barrier()
; template <class Epi, class Sched, bool ALIGN_EPI = false, bool SP2 = false>
; __device__ __forceinline__ void gemm_phase(PG8_LAS unsigned char* lds, const Gemm g, const Sched& S, const Epi& E, int tid_in) {
;     ...
;         for (int t = 0; t < nt; t += 2) {
;             const bool last = (t == nt - 2);
;             const char* a1 = cA + (size_t)(t + 1) * kstep;
;             const char* a2 = last ? nA : cA + (size_t)(t + 2) * kstep; const char* b2 = last ? nB : cB + (size_t)(t + 2) * kstep;
;             const char* a3 = a2 + kstep; const char* b3 = b2 + kstep;
;             if (last && has_next) S.a_ready(nxt);
;             if constexpr (SP2) {
;             PG8_LDB(B0, 0, 0); PG8_LDB(B1, 0, 1); PG8_SCHED; PG8_LDA(At, 0, 0); PG8_STAGE(PG8_SA(1, 1), a1 + hstep, voffA);
;             PG8_WAIT_V(8); PG8_WAIT_L(0); PG8_BAR; PG8_MMA(0, 0, At, B0); PG8_MMA(0, 1, At, B1); PG8_BAR; PG8_SCHED;
;             PG8_LDA(At, 0, 1); PG8_STAGE(PG8_SB(0, 0), b2, voffB); PG8_STAGE(PG8_SB(0, 1), b2 + hstep, voffB); PG8_STAGE(PG8_SA(0, 0), a2, voffA);
;             PG8_WAIT_V(8); PG8_WAIT_L(0); PG8_BAR; PG8_MMA(1, 0, At, B0); PG8_MMA(1, 1, At, B1); PG8_BAR; PG8_SCHED;
.LBB0_1432:
	s_add_u32 s42, s40, 0xfffc0080
	s_addc_u32 s43, s41, -1
	s_add_i32 s79, 0, 0x10000
	s_cmp_eq_u32 s78, 12
	s_cselect_b32 s67, s0, s43
	s_cselect_b32 s66, s1, s42
	s_cselect_b32 s43, s5, s77
	s_cselect_b32 s42, s59, s61
	s_add_i32 s82, 0, 0x14000
	v_add_u32_e32 v142, s79, v210
	v_add_u32_e32 v158, s82, v210
	ds_read_b128 v[114:117], v142
	ds_read_b128 v[118:121], v142 offset:1024
	ds_read_b128 v[138:141], v142 offset:2048
	ds_read_b128 v[142:145], v142 offset:3072
	ds_read_b128 v[146:149], v158
	ds_read_b128 v[150:153], v158 offset:1024
	ds_read_b128 v[154:157], v158 offset:2048
	ds_read_b128 v[158:161], v158 offset:3072
	v_lshl_add_u64 v[184:185], s[40:41], 0, v[168:169]
	s_add_i32 m0, s9, 0xc000
	ds_read_b128 v[172:175], v211
	ds_read_b128 v[176:179], v211 offset:1024
	ds_read_b128 v[180:183], v211 offset:2048
	ds_read_b128 v[190:193], v211 offset:3072
	ds_read_b128 v[194:197], v211 offset:4096
	ds_read_b128 v[198:201], v211 offset:5120
	ds_read_b128 v[202:205], v211 offset:6144
	ds_read_b128 v[212:215], v211 offset:7168
	global_load_lds_dwordx4 v[184:185], off
	v_lshl_add_u64 v[184:185], s[40:41], 0, v[170:171]
	s_add_i32 m0, s9, 0xe000
	s_nop 0
	global_load_lds_dwordx4 v[184:185], off
	s_waitcnt vmcnt(8)
	s_waitcnt lgkmcnt(0)
	s_barrier
	s_setprio 1
	s_waitcnt lgkmcnt(0)
	v_mfma_f32_16x16x32_bf16 v[134:137], v[114:117], v[172:175], v[134:137]
	v_mfma_f32_16x16x32_bf16 v[130:133], v[138:141], v[172:175], v[130:133]
	v_mfma_f32_16x16x32_bf16 v[110:113], v[114:117], v[180:183], v[110:113]
	v_mfma_f32_16x16x32_bf16 v[106:109], v[138:141], v[180:183], v[106:109]
	v_mfma_f32_16x16x32_bf16 v[94:97], v[114:117], v[194:197], v[94:97]
	v_mfma_f32_16x16x32_bf16 v[90:93], v[138:141], v[194:197], v[90:93]
	v_mfma_f32_16x16x32_bf16 v[76:79], v[114:117], v[202:205], v[76:79]
	v_mfma_f32_16x16x32_bf16 v[72:75], v[138:141], v[202:205], v[72:75]
	v_mfma_f32_16x16x32_bf16 v[134:137], v[118:121], v[176:179], v[134:137]
	v_mfma_f32_16x16x32_bf16 v[130:133], v[142:145], v[176:179], v[130:133]
	v_mfma_f32_16x16x32_bf16 v[110:113], v[118:121], v[190:193], v[110:113]
	v_mfma_f32_16x16x32_bf16 v[106:109], v[142:145], v[190:193], v[106:109]
	v_mfma_f32_16x16x32_bf16 v[94:97], v[118:121], v[198:201], v[94:97]
	v_mfma_f32_16x16x32_bf16 v[90:93], v[142:145], v[198:201], v[90:93]
	v_mfma_f32_16x16x32_bf16 v[76:79], v[118:121], v[212:215], v[76:79]
	v_mfma_f32_16x16x32_bf16 v[72:75], v[142:145], v[212:215], v[72:75]
	v_mfma_f32_16x16x32_bf16 v[126:129], v[146:149], v[172:175], v[126:129]
	v_mfma_f32_16x16x32_bf16 v[122:125], v[154:157], v[172:175], v[122:125]
	v_mfma_f32_16x16x32_bf16 v[102:105], v[146:149], v[180:183], v[102:105]
	v_mfma_f32_16x16x32_bf16 v[98:101], v[154:157], v[180:183], v[98:101]
	v_mfma_f32_16x16x32_bf16 v[86:89], v[146:149], v[194:197], v[86:89]
	v_mfma_f32_16x16x32_bf16 v[82:85], v[154:157], v[194:197], v[82:85]
	v_mfma_f32_16x16x32_bf16 v[68:71], v[146:149], v[202:205], v[68:71]
	v_mfma_f32_16x16x32_bf16 v[64:67], v[154:157], v[202:205], v[64:67]
	v_mfma_f32_16x16x32_bf16 v[126:129], v[150:153], v[176:179], v[126:129]
	v_mfma_f32_16x16x32_bf16 v[122:125], v[158:161], v[176:179], v[122:125]
	v_mfma_f32_16x16x32_bf16 v[102:105], v[150:153], v[190:193], v[102:105]
	v_mfma_f32_16x16x32_bf16 v[98:101], v[158:161], v[190:193], v[98:101]
	v_mfma_f32_16x16x32_bf16 v[86:89], v[150:153], v[198:201], v[86:89]
	v_mfma_f32_16x16x32_bf16 v[82:85], v[158:161], v[198:201], v[82:85]
	v_mfma_f32_16x16x32_bf16 v[68:71], v[150:153], v[212:215], v[68:71]
	v_mfma_f32_16x16x32_bf16 v[64:67], v[158:161], v[212:215], v[64:67]
	s_setprio 0
	s_barrier
	s_add_i32 s79, s79, s14
	v_lshl_add_u64 v[184:185], s[42:43], 0, v[80:81]
	s_mov_b32 m0, s79
	ds_read_b128 v[172:175], v211 offset:16384
	ds_read_b128 v[176:179], v211 offset:17408
	ds_read_b128 v[180:183], v211 offset:18432
	ds_read_b128 v[190:193], v211 offset:19456
	ds_read_b128 v[194:197], v211 offset:20480
	ds_read_b128 v[198:201], v211 offset:21504
	ds_read_b128 v[202:205], v211 offset:22528
	ds_read_b128 v[212:215], v211 offset:23552
	global_load_lds_dwordx4 v[184:185], off
	s_add_i32 m0, s79, 0x2000
	s_add_u32 s80, s42, 0x40000
	v_lshl_add_u64 v[186:187], s[42:43], 0, v[166:167]
	s_addc_u32 s81, s43, 0
	s_add_i32 s79, s82, s14
	global_load_lds_dwordx4 v[186:187], off
	v_lshl_add_u64 v[188:189], s[80:81], 0, v[80:81]
	s_mov_b32 m0, s79
	v_lshl_add_u64 v[206:207], s[66:67], 0, v[164:165]
	global_load_lds_dwordx4 v[188:189], off
	v_lshl_add_u64 v[188:189], s[80:81], 0, v[166:167]
	s_add_i32 m0, s79, 0x2000
	s_nop 0
	global_load_lds_dwordx4 v[188:189], off
	v_lshl_add_u64 v[188:189], s[66:67], 0, v[162:163]
	s_mov_b32 m0, s9
	s_nop 0
	global_load_lds_dwordx4 v[188:189], off
	s_mov_b32 m0, s15
	s_nop 0
	global_load_lds_dwordx4 v[206:207], off
	s_waitcnt vmcnt(8)
	s_waitcnt lgkmcnt(0)
	s_barrier
; #define PG8_STAGE(bufoff, gbase, voff) do { _Pragma("unroll") for (int _i = 0; _i < 2; ++_i) \
;         __builtin_amdgcn_global_load_lds((const unsigned*)((const char*)(gbase) + (voff)[_i]), (PG8_LAS unsigned*)(lds + (bufoff) + ldsw + _i * 8192), 16, 0, 0); } while (0)
; #define PG8_LDA(dst, b, h) do { _Pragma("unroll") for (int m = 0; m < 4; ++m) _Pragma("unroll") for (int k = 0; k < 2; ++k) dst[m][k] = *(const PG8_LAS bf16x8*)(lds + PG8_SA(b, h) + aoff + m * 2048 + k * 1024); } while (0)
; #define PG8_LDB(dst, b, h) do { _Pragma("unroll") for (int n = 0; n < 2; ++n) _Pragma("unroll") for (int k = 0; k < 2; ++k) dst[n][k] = *(const PG8_LAS bf16x8*)(lds + PG8_SB(b, h) + boff + n * 2048 + k * 1024); } while (0)
; #define PG8_MMA(ai, bj, At, Bt) do { __builtin_amdgcn_s_setprio(1); _Pragma("unroll") for (int m = 0; m < 4; ++m) _Pragma("unroll") for (int n = 0; n < 2; ++n) _Pragma("unroll") for (int k = 0; k < 2; ++k) \
;         acc[ai][bj][m][n] = __builtin_amdgcn_mfma_f32_16x16x32_bf16(Bt[n][k], At[m][k], acc[ai][bj][m][n], 0, 0, 0); __builtin_amdgcn_s_setprio(0); } while (0)
; #define PG8_WAIT_V(n) asm volatile("s_waitcnt vmcnt(" #n ")" ::: "memory")
; #define PG8_WAIT_L(n) asm volatile("s_waitcnt lgkmcnt(" #n ")" ::: "memory")
; #define PG8_BAR __builtin_amdgcn_s_barrier()
; #define PG8_SCHED __builtin_amdgcn_sched_barrier(0)
; template <class Epi, class Sched, bool ALIGN_EPI = false, bool SP2 = false>
; __device__ __forceinline__ void gemm_phase(PG8_LAS unsigned char* lds, const Gemm g, const Sched& S, const Epi& E, int tid_in) {
;     ...
;             PG8_WAIT_V(8); PG8_WAIT_L(0); PG8_BAR; PG8_MMA(1, 0, At, B0); PG8_MMA(1, 1, At, B1); PG8_BAR; PG8_SCHED;
;             PG8_LDB(B0, 1, 0); PG8_LDB(B1, 1, 1); PG8_SCHED; PG8_LDA(At, 1, 0); PG8_STAGE(PG8_SA(0, 1), a2 + hstep, voffA);
;             PG8_WAIT_V(8); PG8_WAIT_L(0); PG8_BAR; PG8_MMA(0, 0, At, B0); PG8_MMA(0, 1, At, B1); PG8_BAR; PG8_SCHED;
	s_setprio 1
	s_waitcnt lgkmcnt(0)
	v_mfma_f32_16x16x32_bf16 v[60:63], v[114:117], v[172:175], v[60:63]
	v_mfma_f32_16x16x32_bf16 v[56:59], v[138:141], v[172:175], v[56:59]
	v_mfma_f32_16x16x32_bf16 v[44:47], v[114:117], v[180:183], v[44:47]
	v_mfma_f32_16x16x32_bf16 v[40:43], v[138:141], v[180:183], v[40:43]
	v_mfma_f32_16x16x32_bf16 v[28:31], v[114:117], v[194:197], v[28:31]
	v_mfma_f32_16x16x32_bf16 v[24:27], v[138:141], v[194:197], v[24:27]
	v_mfma_f32_16x16x32_bf16 v[12:15], v[114:117], v[202:205], v[12:15]
	v_mfma_f32_16x16x32_bf16 v[8:11], v[138:141], v[202:205], v[8:11]
	v_mfma_f32_16x16x32_bf16 v[60:63], v[118:121], v[176:179], v[60:63]
	v_mfma_f32_16x16x32_bf16 v[56:59], v[142:145], v[176:179], v[56:59]
	v_mfma_f32_16x16x32_bf16 v[44:47], v[118:121], v[190:193], v[44:47]
	v_mfma_f32_16x16x32_bf16 v[40:43], v[142:145], v[190:193], v[40:43]
	v_mfma_f32_16x16x32_bf16 v[28:31], v[118:121], v[198:201], v[28:31]
	v_mfma_f32_16x16x32_bf16 v[24:27], v[142:145], v[198:201], v[24:27]
	v_mfma_f32_16x16x32_bf16 v[12:15], v[118:121], v[212:215], v[12:15]
	v_mfma_f32_16x16x32_bf16 v[8:11], v[142:145], v[212:215], v[8:11]
	v_mfma_f32_16x16x32_bf16 v[52:55], v[146:149], v[172:175], v[52:55]
	v_mfma_f32_16x16x32_bf16 v[48:51], v[154:157], v[172:175], v[48:51]
	v_mfma_f32_16x16x32_bf16 v[36:39], v[146:149], v[180:183], v[36:39]
	v_mfma_f32_16x16x32_bf16 v[32:35], v[154:157], v[180:183], v[32:35]
	v_mfma_f32_16x16x32_bf16 v[20:23], v[146:149], v[194:197], v[20:23]
	v_mfma_f32_16x16x32_bf16 v[16:19], v[154:157], v[194:197], v[16:19]
	v_mfma_f32_16x16x32_bf16 v[4:7], v[146:149], v[202:205], v[4:7]
	v_mfma_f32_16x16x32_bf16 v[0:3], v[154:157], v[202:205], v[0:3]
	v_mfma_f32_16x16x32_bf16 v[52:55], v[150:153], v[176:179], v[52:55]
	v_mfma_f32_16x16x32_bf16 v[48:51], v[158:161], v[176:179], v[48:51]
	v_mfma_f32_16x16x32_bf16 v[36:39], v[150:153], v[190:193], v[36:39]
	v_mfma_f32_16x16x32_bf16 v[32:35], v[158:161], v[190:193], v[32:35]
	v_mfma_f32_16x16x32_bf16 v[20:23], v[150:153], v[198:201], v[20:23]
	v_mfma_f32_16x16x32_bf16 v[16:19], v[158:161], v[198:201], v[16:19]
	v_mfma_f32_16x16x32_bf16 v[4:7], v[150:153], v[212:215], v[4:7]
	v_mfma_f32_16x16x32_bf16 v[0:3], v[158:161], v[212:215], v[0:3]
	s_setprio 0
	s_barrier
	s_add_i32 s79, 0, 0x18000
	s_add_i32 s80, 0, 0x1c000
	v_add_u32_e32 v142, s79, v210
	v_add_u32_e32 v158, s80, v210
	ds_read_b128 v[114:117], v142
	ds_read_b128 v[118:121], v142 offset:1024
	ds_read_b128 v[138:141], v142 offset:2048
	ds_read_b128 v[142:145], v142 offset:3072
	ds_read_b128 v[146:149], v158
	ds_read_b128 v[150:153], v158 offset:1024
	ds_read_b128 v[154:157], v158 offset:2048
	ds_read_b128 v[158:161], v158 offset:3072
	s_add_u32 s66, s66, 0x40000
	s_addc_u32 s67, s67, 0
	s_mov_b32 m0, s16
	v_lshl_add_u64 v[226:227], s[66:67], 0, v[162:163]
	ds_read_b128 v[172:175], v211 offset:32768
	ds_read_b128 v[176:179], v211 offset:33792
	ds_read_b128 v[180:183], v211 offset:34816
	ds_read_b128 v[190:193], v211 offset:35840
	ds_read_b128 v[194:197], v211 offset:36864
	ds_read_b128 v[198:201], v211 offset:37888
	ds_read_b128 v[202:205], v211 offset:38912
	ds_read_b128 v[212:215], v211 offset:39936
	global_load_lds_dwordx4 v[226:227], off
	v_lshl_add_u64 v[226:227], s[66:67], 0, v[164:165]
	s_mov_b32 m0, s17
	s_nop 0
	global_load_lds_dwordx4 v[226:227], off
	s_waitcnt vmcnt(8)
	s_waitcnt lgkmcnt(0)
	s_barrier
	s_setprio 1
	s_waitcnt lgkmcnt(0)
	v_mfma_f32_16x16x32_bf16 v[134:137], v[114:117], v[172:175], v[134:137]
	v_mfma_f32_16x16x32_bf16 v[130:133], v[138:141], v[172:175], v[130:133]
	v_mfma_f32_16x16x32_bf16 v[110:113], v[114:117], v[180:183], v[110:113]
	v_mfma_f32_16x16x32_bf16 v[106:109], v[138:141], v[180:183], v[106:109]
	v_mfma_f32_16x16x32_bf16 v[94:97], v[114:117], v[194:197], v[94:97]
	v_mfma_f32_16x16x32_bf16 v[90:93], v[138:141], v[194:197], v[90:93]
	v_mfma_f32_16x16x32_bf16 v[76:79], v[114:117], v[202:205], v[76:79]
	v_mfma_f32_16x16x32_bf16 v[72:75], v[138:141], v[202:205], v[72:75]
	v_mfma_f32_16x16x32_bf16 v[134:137], v[118:121], v[176:179], v[134:137]
	v_mfma_f32_16x16x32_bf16 v[130:133], v[142:145], v[176:179], v[130:133]
	v_mfma_f32_16x16x32_bf16 v[110:113], v[118:121], v[190:193], v[110:113]
	v_mfma_f32_16x16x32_bf16 v[106:109], v[142:145], v[190:193], v[106:109]
	v_mfma_f32_16x16x32_bf16 v[94:97], v[118:121], v[198:201], v[94:97]
	v_mfma_f32_16x16x32_bf16 v[90:93], v[142:145], v[198:201], v[90:93]
	v_mfma_f32_16x16x32_bf16 v[76:79], v[118:121], v[212:215], v[76:79]
	v_mfma_f32_16x16x32_bf16 v[72:75], v[142:145], v[212:215], v[72:75]
	v_mfma_f32_16x16x32_bf16 v[126:129], v[146:149], v[172:175], v[126:129]
	v_mfma_f32_16x16x32_bf16 v[122:125], v[154:157], v[172:175], v[122:125]
	v_mfma_f32_16x16x32_bf16 v[102:105], v[146:149], v[180:183], v[102:105]
	v_mfma_f32_16x16x32_bf16 v[98:101], v[154:157], v[180:183], v[98:101]
	v_mfma_f32_16x16x32_bf16 v[86:89], v[146:149], v[194:197], v[86:89]
	v_mfma_f32_16x16x32_bf16 v[82:85], v[154:157], v[194:197], v[82:85]
	v_mfma_f32_16x16x32_bf16 v[68:71], v[146:149], v[202:205], v[68:71]
	v_mfma_f32_16x16x32_bf16 v[64:67], v[154:157], v[202:205], v[64:67]
	v_mfma_f32_16x16x32_bf16 v[126:129], v[150:153], v[176:179], v[126:129]
	v_mfma_f32_16x16x32_bf16 v[122:125], v[158:161], v[176:179], v[122:125]
	v_mfma_f32_16x16x32_bf16 v[102:105], v[150:153], v[190:193], v[102:105]
	v_mfma_f32_16x16x32_bf16 v[98:101], v[158:161], v[190:193], v[98:101]
	v_mfma_f32_16x16x32_bf16 v[86:89], v[150:153], v[198:201], v[86:89]
	v_mfma_f32_16x16x32_bf16 v[82:85], v[158:161], v[198:201], v[82:85]
	v_mfma_f32_16x16x32_bf16 v[68:71], v[150:153], v[212:215], v[68:71]
	v_mfma_f32_16x16x32_bf16 v[64:67], v[158:161], v[212:215], v[64:67]
	s_setprio 0
	s_barrier
; #define PG8_STAGE(bufoff, gbase, voff) do { _Pragma("unroll") for (int _i = 0; _i < 2; ++_i) \
;         __builtin_amdgcn_global_load_lds((const unsigned*)((const char*)(gbase) + (voff)[_i]), (PG8_LAS unsigned*)(lds + (bufoff) + ldsw + _i * 8192), 16, 0, 0); } while (0)
; #define PG8_LDA(dst, b, h) do { _Pragma("unroll") for (int m = 0; m < 4; ++m) _Pragma("unroll") for (int k = 0; k < 2; ++k) dst[m][k] = *(const PG8_LAS bf16x8*)(lds + PG8_SA(b, h) + aoff + m * 2048 + k * 1024); } while (0)
; #define PG8_MMA(ai, bj, At, Bt) do { __builtin_amdgcn_s_setprio(1); _Pragma("unroll") for (int m = 0; m < 4; ++m) _Pragma("unroll") for (int n = 0; n < 2; ++n) _Pragma("unroll") for (int k = 0; k < 2; ++k) \
;         acc[ai][bj][m][n] = __builtin_amdgcn_mfma_f32_16x16x32_bf16(Bt[n][k], At[m][k], acc[ai][bj][m][n], 0, 0, 0); __builtin_amdgcn_s_setprio(0); } while (0)
; #define PG8_WAIT_V(n) asm volatile("s_waitcnt vmcnt(" #n ")" ::: "memory")
; #define PG8_WAIT_L(n) asm volatile("s_waitcnt lgkmcnt(" #n ")" ::: "memory")
; #define PG8_BAR __builtin_amdgcn_s_barrier()
; #define PG8_SCHED __builtin_amdgcn_sched_barrier(0)
; template <class Epi, class Sched, bool ALIGN_EPI = false, bool SP2 = false>
; __device__ __forceinline__ void gemm_phase(PG8_LAS unsigned char* lds, const Gemm g, const Sched& S, const Epi& E, int tid_in) {
;     ...
;         for (int t = 0; t < nt; t += 2) {
;             const bool last = (t == nt - 2);
;             const char* a1 = cA + (size_t)(t + 1) * kstep;
;             const char* a2 = last ? nA : cA + (size_t)(t + 2) * kstep; const char* b2 = last ? nB : cB + (size_t)(t + 2) * kstep;
;     ...
;             PG8_LDA(At, 1, 1); PG8_STAGE(PG8_SB(1, 0), b3, voffB); PG8_STAGE(PG8_SB(1, 1), b3 + hstep, voffB); PG8_STAGE(PG8_SA(1, 0), a3, voffA);
;             PG8_WAIT_V(8); PG8_WAIT_L(0); PG8_BAR; PG8_MMA(1, 0, At, B0); PG8_MMA(1, 1, At, B1); PG8_BAR; PG8_SCHED;
	s_add_i32 s66, s79, s14
	v_lshl_add_u64 v[184:185], v[184:185], 0, s[6:7]
	s_mov_b32 m0, s66
	ds_read_b128 v[172:175], v211 offset:49152
	ds_read_b128 v[176:179], v211 offset:50176
	ds_read_b128 v[180:183], v211 offset:51200
	ds_read_b128 v[190:193], v211 offset:52224
	ds_read_b128 v[194:197], v211 offset:53248
	ds_read_b128 v[198:201], v211 offset:54272
	ds_read_b128 v[202:205], v211 offset:55296
	ds_read_b128 v[212:215], v211 offset:56320
	global_load_lds_dwordx4 v[184:185], off
	s_add_i32 m0, s66, 0x2000
	s_add_u32 s42, s42, 0x40080
	v_lshl_add_u64 v[184:185], v[186:187], 0, s[6:7]
	s_addc_u32 s43, s43, 0
	s_add_i32 s66, s80, s14
	global_load_lds_dwordx4 v[184:185], off
	v_lshl_add_u64 v[184:185], s[42:43], 0, v[80:81]
	s_mov_b32 m0, s66
	s_nop 0
	global_load_lds_dwordx4 v[184:185], off
	v_lshl_add_u64 v[184:185], s[42:43], 0, v[166:167]
	s_add_i32 m0, s66, 0x2000
	s_nop 0
	global_load_lds_dwordx4 v[184:185], off
	v_lshl_add_u64 v[184:185], v[188:189], 0, s[6:7]
	s_mov_b32 m0, s69
	s_nop 0
	global_load_lds_dwordx4 v[184:185], off
	v_lshl_add_u64 v[184:185], v[206:207], 0, s[6:7]
	s_mov_b32 m0, s70
	s_nop 0
	global_load_lds_dwordx4 v[184:185], off
	s_waitcnt vmcnt(8)
	s_waitcnt lgkmcnt(0)
	s_barrier
	s_setprio 1
	s_waitcnt lgkmcnt(0)
	v_mfma_f32_16x16x32_bf16 v[60:63], v[114:117], v[172:175], v[60:63]
	v_mfma_f32_16x16x32_bf16 v[56:59], v[138:141], v[172:175], v[56:59]
	v_mfma_f32_16x16x32_bf16 v[44:47], v[114:117], v[180:183], v[44:47]
	v_mfma_f32_16x16x32_bf16 v[40:43], v[138:141], v[180:183], v[40:43]
	v_mfma_f32_16x16x32_bf16 v[28:31], v[114:117], v[194:197], v[28:31]
	v_mfma_f32_16x16x32_bf16 v[24:27], v[138:141], v[194:197], v[24:27]
	v_mfma_f32_16x16x32_bf16 v[12:15], v[114:117], v[202:205], v[12:15]
	v_mfma_f32_16x16x32_bf16 v[8:11], v[138:141], v[202:205], v[8:11]
	v_mfma_f32_16x16x32_bf16 v[60:63], v[118:121], v[176:179], v[60:63]
	v_mfma_f32_16x16x32_bf16 v[56:59], v[142:145], v[176:179], v[56:59]
	v_mfma_f32_16x16x32_bf16 v[44:47], v[118:121], v[190:193], v[44:47]
	v_mfma_f32_16x16x32_bf16 v[40:43], v[142:145], v[190:193], v[40:43]
	v_mfma_f32_16x16x32_bf16 v[28:31], v[118:121], v[198:201], v[28:31]
	v_mfma_f32_16x16x32_bf16 v[24:27], v[142:145], v[198:201], v[24:27]
	v_mfma_f32_16x16x32_bf16 v[12:15], v[118:121], v[212:215], v[12:15]
	v_mfma_f32_16x16x32_bf16 v[8:11], v[142:145], v[212:215], v[8:11]
	v_mfma_f32_16x16x32_bf16 v[52:55], v[146:149], v[172:175], v[52:55]
	v_mfma_f32_16x16x32_bf16 v[48:51], v[154:157], v[172:175], v[48:51]
	v_mfma_f32_16x16x32_bf16 v[36:39], v[146:149], v[180:183], v[36:39]
	v_mfma_f32_16x16x32_bf16 v[32:35], v[154:157], v[180:183], v[32:35]
	v_mfma_f32_16x16x32_bf16 v[20:23], v[146:149], v[194:197], v[20:23]
	v_mfma_f32_16x16x32_bf16 v[16:19], v[154:157], v[194:197], v[16:19]
	v_mfma_f32_16x16x32_bf16 v[4:7], v[146:149], v[202:205], v[4:7]
	v_mfma_f32_16x16x32_bf16 v[0:3], v[154:157], v[202:205], v[0:3]
	v_mfma_f32_16x16x32_bf16 v[52:55], v[150:153], v[176:179], v[52:55]
	v_mfma_f32_16x16x32_bf16 v[48:51], v[158:161], v[176:179], v[48:51]
	v_mfma_f32_16x16x32_bf16 v[36:39], v[150:153], v[190:193], v[36:39]
	v_mfma_f32_16x16x32_bf16 v[32:35], v[158:161], v[190:193], v[32:35]
	v_mfma_f32_16x16x32_bf16 v[20:23], v[150:153], v[198:201], v[20:23]
	v_mfma_f32_16x16x32_bf16 v[16:19], v[158:161], v[198:201], v[16:19]
	v_mfma_f32_16x16x32_bf16 v[4:7], v[150:153], v[212:215], v[4:7]
	v_mfma_f32_16x16x32_bf16 v[0:3], v[158:161], v[212:215], v[0:3]
	s_setprio 0
	s_barrier
	s_add_i32 s78, s78, 2
	s_add_u32 s40, s40, 0x100
	s_addc_u32 s41, s41, 0
	s_add_u32 s61, s61, 0x100
	s_addc_u32 s77, s77, 0
	s_cmp_gt_u32 s78, 13
	s_cbranch_scc0 .LBB0_1432
	s_and_b64 vcc, exec, s[54:55]
	s_cbranch_vccz .LBB0_1435
	s_barrier

; #define PG8_STAGE(bufoff, gbase, voff) do { _Pragma("unroll") for (int _i = 0; _i < 2; ++_i) \
;         __builtin_amdgcn_global_load_lds((const unsigned*)((const char*)(gbase) + (voff)[_i]), (PG8_LAS unsigned*)(lds + (bufoff) + ldsw + _i * 8192), 16, 0, 0); } while (0)
; #define PG8_LDA(dst, b, h) do { _Pragma("unroll") for (int m = 0; m < 4; ++m) _Pragma("unroll") for (int k = 0; k < 2; ++k) dst[m][k] = *(const PG8_LAS bf16x8*)(lds + PG8_SA(b, h) + aoff + m * 2048 + k * 1024); } while (0)
; #define PG8_LDB(dst, b, h) do { _Pragma("unroll") for (int n = 0; n < 2; ++n) _Pragma("unroll") for (int k = 0; k < 2; ++k) dst[n][k] = *(const PG8_LAS bf16x8*)(lds + PG8_SB(b, h) + boff + n * 2048 + k * 1024); } while (0)
; #define PG8_MMA(ai, bj, At, Bt) do { __builtin_amdgcn_s_setprio(1); _Pragma("unroll") for (int m = 0; m < 4; ++m) _Pragma("unroll") for (int n = 0; n < 2; ++n) _Pragma("unroll") for (int k = 0; k < 2; ++k) \
;         acc[ai][bj][m][n] = __builtin_amdgcn_mfma_f32_16x16x32_bf16(Bt[n][k], At[m][k], acc[ai][bj][m][n], 0, 0, 0); __builtin_amdgcn_s_setprio(0); } while (0)
; #define PG8_WAIT_V(n) asm volatile("s_waitcnt vmcnt(" #n ")" ::: "memory")
; #define PG8_BAR __builtin_amdgcn_s_barrier()
; template <class Epi, class Sched, bool ALIGN_EPI = false, bool SP2 = false>
; __device__ __forceinline__ void gemm_phase(PG8_LAS unsigned char* lds, const Gemm g, const Sched& S, const Epi& E, int tid_in) {
;     ...
;         for (int t = 0; t < nt; t += 2) {
;             const bool last = (t == nt - 2);
;             const char* a1 = cA + (size_t)(t + 1) * kstep;
;             const char* a2 = last ? nA : cA + (size_t)(t + 2) * kstep; const char* b2 = last ? nB : cB + (size_t)(t + 2) * kstep;
;             const char* a3 = a2 + kstep; const char* b3 = b2 + kstep;
;             if (last && has_next) S.a_ready(nxt);
;             if constexpr (SP2) {
;             PG8_LDB(B0, 0, 0); PG8_LDB(B1, 0, 1); PG8_SCHED; PG8_LDA(At, 0, 0); PG8_STAGE(PG8_SA(1, 1), a1 + hstep, voffA);
;             PG8_WAIT_V(8); PG8_WAIT_L(0); PG8_BAR; PG8_MMA(0, 0, At, B0); PG8_MMA(0, 1, At, B1); PG8_BAR; PG8_SCHED;
;             PG8_LDA(At, 0, 1); PG8_STAGE(PG8_SB(0, 0), b2, voffB); PG8_STAGE(PG8_SB(0, 1), b2 + hstep, voffB); PG8_STAGE(PG8_SA(0, 0), a2, voffA);
;             PG8_WAIT_V(8); PG8_WAIT_L(0); PG8_BAR; PG8_MMA(1, 0, At, B0); PG8_MMA(1, 1, At, B1); PG8_BAR; PG8_SCHED;
.LBB0_1601:
	s_add_u32 s54, s52, 0xfffc0080
	s_addc_u32 s55, s53, -1
	s_add_i32 s72, 0, 0x10000
	s_cmp_eq_u32 s71, 12
	s_cselect_b32 s57, s0, s55
	s_cselect_b32 s56, s1, s54
	s_cselect_b32 s55, s43, s70
	s_cselect_b32 s54, s47, s69
	s_add_i32 s74, 0, 0x14000
	v_add_u32_e32 v76, s72, v182
	v_add_u32_e32 v94, s74, v182
	ds_read_b128 v[60:63], v76
	ds_read_b128 v[64:67], v76 offset:1024
	ds_read_b128 v[72:75], v76 offset:2048
	ds_read_b128 v[76:79], v76 offset:3072
	ds_read_b128 v[82:85], v94
	ds_read_b128 v[86:89], v94 offset:1024
	ds_read_b128 v[90:93], v94 offset:2048
	ds_read_b128 v[94:97], v94 offset:3072
	v_lshl_add_u64 v[208:209], s[52:53], 0, v[172:173]
	s_add_i32 m0, s18, 0xc000
	ds_read_b128 v[162:165], v183
	ds_read_b128 v[176:179], v183 offset:1024
	ds_read_b128 v[184:187], v183 offset:2048
	ds_read_b128 v[188:191], v183 offset:3072
	ds_read_b128 v[192:195], v183 offset:4096
	ds_read_b128 v[196:199], v183 offset:5120
	ds_read_b128 v[200:203], v183 offset:6144
	ds_read_b128 v[204:207], v183 offset:7168
	global_load_lds_dwordx4 v[208:209], off
	v_lshl_add_u64 v[208:209], s[52:53], 0, v[174:175]
	s_add_i32 m0, s18, 0xe000
	s_nop 0
	global_load_lds_dwordx4 v[208:209], off
	s_waitcnt vmcnt(8)
	s_waitcnt lgkmcnt(0)
	s_barrier
	s_setprio 1
	s_waitcnt lgkmcnt(0)
	v_mfma_f32_16x16x32_bf16 v[158:161], v[60:63], v[162:165], v[158:161]
	v_mfma_f32_16x16x32_bf16 v[154:157], v[72:75], v[162:165], v[154:157]
	v_mfma_f32_16x16x32_bf16 v[142:145], v[60:63], v[184:187], v[142:145]
	v_mfma_f32_16x16x32_bf16 v[138:141], v[72:75], v[184:187], v[138:141]
	v_mfma_f32_16x16x32_bf16 v[126:129], v[60:63], v[192:195], v[126:129]
	v_mfma_f32_16x16x32_bf16 v[122:125], v[72:75], v[192:195], v[122:125]
	v_mfma_f32_16x16x32_bf16 v[110:113], v[60:63], v[200:203], v[110:113]
	v_mfma_f32_16x16x32_bf16 v[106:109], v[72:75], v[200:203], v[106:109]
	v_mfma_f32_16x16x32_bf16 v[158:161], v[64:67], v[176:179], v[158:161]
	v_mfma_f32_16x16x32_bf16 v[154:157], v[76:79], v[176:179], v[154:157]
	v_mfma_f32_16x16x32_bf16 v[142:145], v[64:67], v[188:191], v[142:145]
	v_mfma_f32_16x16x32_bf16 v[138:141], v[76:79], v[188:191], v[138:141]
	v_mfma_f32_16x16x32_bf16 v[126:129], v[64:67], v[196:199], v[126:129]
	v_mfma_f32_16x16x32_bf16 v[122:125], v[76:79], v[196:199], v[122:125]
	v_mfma_f32_16x16x32_bf16 v[110:113], v[64:67], v[204:207], v[110:113]
	v_mfma_f32_16x16x32_bf16 v[106:109], v[76:79], v[204:207], v[106:109]
	v_mfma_f32_16x16x32_bf16 v[150:153], v[82:85], v[162:165], v[150:153]
	v_mfma_f32_16x16x32_bf16 v[146:149], v[90:93], v[162:165], v[146:149]
	v_mfma_f32_16x16x32_bf16 v[134:137], v[82:85], v[184:187], v[134:137]
	v_mfma_f32_16x16x32_bf16 v[130:133], v[90:93], v[184:187], v[130:133]
	v_mfma_f32_16x16x32_bf16 v[118:121], v[82:85], v[192:195], v[118:121]
	v_mfma_f32_16x16x32_bf16 v[114:117], v[90:93], v[192:195], v[114:117]
	v_mfma_f32_16x16x32_bf16 v[102:105], v[82:85], v[200:203], v[102:105]
	v_mfma_f32_16x16x32_bf16 v[98:101], v[90:93], v[200:203], v[98:101]
	v_mfma_f32_16x16x32_bf16 v[150:153], v[86:89], v[176:179], v[150:153]
	v_mfma_f32_16x16x32_bf16 v[146:149], v[94:97], v[176:179], v[146:149]
	v_mfma_f32_16x16x32_bf16 v[134:137], v[86:89], v[188:191], v[134:137]
	v_mfma_f32_16x16x32_bf16 v[130:133], v[94:97], v[188:191], v[130:133]
	v_mfma_f32_16x16x32_bf16 v[118:121], v[86:89], v[196:199], v[118:121]
	v_mfma_f32_16x16x32_bf16 v[114:117], v[94:97], v[196:199], v[114:117]
	v_mfma_f32_16x16x32_bf16 v[102:105], v[86:89], v[204:207], v[102:105]
	v_mfma_f32_16x16x32_bf16 v[98:101], v[94:97], v[204:207], v[98:101]
	s_setprio 0
	s_barrier
	s_add_i32 s72, s72, s17
	v_lshl_add_u64 v[208:209], s[54:55], 0, v[80:81]
	s_mov_b32 m0, s72
	ds_read_b128 v[162:165], v183 offset:16384
	ds_read_b128 v[176:179], v183 offset:17408
	ds_read_b128 v[184:187], v183 offset:18432
	ds_read_b128 v[188:191], v183 offset:19456
	ds_read_b128 v[192:195], v183 offset:20480
	ds_read_b128 v[196:199], v183 offset:21504
	ds_read_b128 v[200:203], v183 offset:22528
	ds_read_b128 v[204:207], v183 offset:23552
	global_load_lds_dwordx4 v[208:209], off
	s_add_i32 m0, s72, 0x2000
	s_add_u32 s72, s54, 0x40000
	v_lshl_add_u64 v[210:211], s[54:55], 0, v[170:171]
	s_addc_u32 s73, s55, 0
	s_add_i32 s74, s74, s17
	global_load_lds_dwordx4 v[210:211], off
	v_lshl_add_u64 v[212:213], s[72:73], 0, v[80:81]
	s_mov_b32 m0, s74
	v_lshl_add_u64 v[214:215], s[56:57], 0, v[168:169]
	global_load_lds_dwordx4 v[212:213], off
	v_lshl_add_u64 v[212:213], s[72:73], 0, v[170:171]
	s_add_i32 m0, s74, 0x2000
	s_nop 0
	global_load_lds_dwordx4 v[212:213], off
	v_lshl_add_u64 v[212:213], s[56:57], 0, v[166:167]
	s_mov_b32 m0, s18
	s_nop 0
	global_load_lds_dwordx4 v[212:213], off
	s_mov_b32 m0, s19
	s_nop 0
	global_load_lds_dwordx4 v[214:215], off
	s_waitcnt vmcnt(8)
	s_waitcnt lgkmcnt(0)
	s_barrier
; #define PG8_STAGE(bufoff, gbase, voff) do { _Pragma("unroll") for (int _i = 0; _i < 2; ++_i) \
;         __builtin_amdgcn_global_load_lds((const unsigned*)((const char*)(gbase) + (voff)[_i]), (PG8_LAS unsigned*)(lds + (bufoff) + ldsw + _i * 8192), 16, 0, 0); } while (0)
; #define PG8_LDA(dst, b, h) do { _Pragma("unroll") for (int m = 0; m < 4; ++m) _Pragma("unroll") for (int k = 0; k < 2; ++k) dst[m][k] = *(const PG8_LAS bf16x8*)(lds + PG8_SA(b, h) + aoff + m * 2048 + k * 1024); } while (0)
; #define PG8_LDB(dst, b, h) do { _Pragma("unroll") for (int n = 0; n < 2; ++n) _Pragma("unroll") for (int k = 0; k < 2; ++k) dst[n][k] = *(const PG8_LAS bf16x8*)(lds + PG8_SB(b, h) + boff + n * 2048 + k * 1024); } while (0)
; #define PG8_MMA(ai, bj, At, Bt) do { __builtin_amdgcn_s_setprio(1); _Pragma("unroll") for (int m = 0; m < 4; ++m) _Pragma("unroll") for (int n = 0; n < 2; ++n) _Pragma("unroll") for (int k = 0; k < 2; ++k) \
;         acc[ai][bj][m][n] = __builtin_amdgcn_mfma_f32_16x16x32_bf16(Bt[n][k], At[m][k], acc[ai][bj][m][n], 0, 0, 0); __builtin_amdgcn_s_setprio(0); } while (0)
; #define PG8_WAIT_V(n) asm volatile("s_waitcnt vmcnt(" #n ")" ::: "memory")
; #define PG8_WAIT_L(n) asm volatile("s_waitcnt lgkmcnt(" #n ")" ::: "memory")
; #define PG8_BAR __builtin_amdgcn_s_barrier()
; #define PG8_SCHED __builtin_amdgcn_sched_barrier(0)
; template <class Epi, class Sched, bool ALIGN_EPI = false, bool SP2 = false>
; __device__ __forceinline__ void gemm_phase(PG8_LAS unsigned char* lds, const Gemm g, const Sched& S, const Epi& E, int tid_in) {
;     ...
;             PG8_WAIT_V(8); PG8_WAIT_L(0); PG8_BAR; PG8_MMA(1, 0, At, B0); PG8_MMA(1, 1, At, B1); PG8_BAR; PG8_SCHED;
;             PG8_LDB(B0, 1, 0); PG8_LDB(B1, 1, 1); PG8_SCHED; PG8_LDA(At, 1, 0); PG8_STAGE(PG8_SA(0, 1), a2 + hstep, voffA);
;             PG8_WAIT_V(8); PG8_WAIT_L(0); PG8_BAR; PG8_MMA(0, 0, At, B0); PG8_MMA(0, 1, At, B1); PG8_BAR; PG8_SCHED;
	s_setprio 1
	s_waitcnt lgkmcnt(0)
	v_mfma_f32_16x16x32_bf16 v[68:71], v[60:63], v[162:165], v[68:71]
	v_mfma_f32_16x16x32_bf16 v[56:59], v[72:75], v[162:165], v[56:59]
	v_mfma_f32_16x16x32_bf16 v[44:47], v[60:63], v[184:187], v[44:47]
	v_mfma_f32_16x16x32_bf16 v[40:43], v[72:75], v[184:187], v[40:43]
	v_mfma_f32_16x16x32_bf16 v[28:31], v[60:63], v[192:195], v[28:31]
	v_mfma_f32_16x16x32_bf16 v[24:27], v[72:75], v[192:195], v[24:27]
	v_mfma_f32_16x16x32_bf16 v[12:15], v[60:63], v[200:203], v[12:15]
	v_mfma_f32_16x16x32_bf16 v[8:11], v[72:75], v[200:203], v[8:11]
	v_mfma_f32_16x16x32_bf16 v[68:71], v[64:67], v[176:179], v[68:71]
	v_mfma_f32_16x16x32_bf16 v[56:59], v[76:79], v[176:179], v[56:59]
	v_mfma_f32_16x16x32_bf16 v[44:47], v[64:67], v[188:191], v[44:47]
	v_mfma_f32_16x16x32_bf16 v[40:43], v[76:79], v[188:191], v[40:43]
	v_mfma_f32_16x16x32_bf16 v[28:31], v[64:67], v[196:199], v[28:31]
	v_mfma_f32_16x16x32_bf16 v[24:27], v[76:79], v[196:199], v[24:27]
	v_mfma_f32_16x16x32_bf16 v[12:15], v[64:67], v[204:207], v[12:15]
	v_mfma_f32_16x16x32_bf16 v[8:11], v[76:79], v[204:207], v[8:11]
	v_mfma_f32_16x16x32_bf16 v[52:55], v[82:85], v[162:165], v[52:55]
	v_mfma_f32_16x16x32_bf16 v[48:51], v[90:93], v[162:165], v[48:51]
	v_mfma_f32_16x16x32_bf16 v[36:39], v[82:85], v[184:187], v[36:39]
	v_mfma_f32_16x16x32_bf16 v[32:35], v[90:93], v[184:187], v[32:35]
	v_mfma_f32_16x16x32_bf16 v[20:23], v[82:85], v[192:195], v[20:23]
	v_mfma_f32_16x16x32_bf16 v[16:19], v[90:93], v[192:195], v[16:19]
	v_mfma_f32_16x16x32_bf16 v[4:7], v[82:85], v[200:203], v[4:7]
	v_mfma_f32_16x16x32_bf16 v[0:3], v[90:93], v[200:203], v[0:3]
	v_mfma_f32_16x16x32_bf16 v[52:55], v[86:89], v[176:179], v[52:55]
	v_mfma_f32_16x16x32_bf16 v[48:51], v[94:97], v[176:179], v[48:51]
	v_mfma_f32_16x16x32_bf16 v[36:39], v[86:89], v[188:191], v[36:39]
	v_mfma_f32_16x16x32_bf16 v[32:35], v[94:97], v[188:191], v[32:35]
	v_mfma_f32_16x16x32_bf16 v[20:23], v[86:89], v[196:199], v[20:23]
	v_mfma_f32_16x16x32_bf16 v[16:19], v[94:97], v[196:199], v[16:19]
	v_mfma_f32_16x16x32_bf16 v[4:7], v[86:89], v[204:207], v[4:7]
	v_mfma_f32_16x16x32_bf16 v[0:3], v[94:97], v[204:207], v[0:3]
	s_setprio 0
	s_barrier
	s_add_i32 s72, 0, 0x18000
	s_add_i32 s73, 0, 0x1c000
	v_add_u32_e32 v76, s72, v182
	v_add_u32_e32 v94, s73, v182
	ds_read_b128 v[60:63], v76
	ds_read_b128 v[64:67], v76 offset:1024
	ds_read_b128 v[72:75], v76 offset:2048
	ds_read_b128 v[76:79], v76 offset:3072
	ds_read_b128 v[82:85], v94
	ds_read_b128 v[86:89], v94 offset:1024
	ds_read_b128 v[90:93], v94 offset:2048
	ds_read_b128 v[94:97], v94 offset:3072
	s_add_u32 s56, s56, 0x40000
	s_addc_u32 s57, s57, 0
	s_mov_b32 m0, s58
	v_lshl_add_u64 v[226:227], s[56:57], 0, v[166:167]
	ds_read_b128 v[162:165], v183 offset:32768
	ds_read_b128 v[176:179], v183 offset:33792
	ds_read_b128 v[184:187], v183 offset:34816
	ds_read_b128 v[188:191], v183 offset:35840
	ds_read_b128 v[192:195], v183 offset:36864
	ds_read_b128 v[196:199], v183 offset:37888
	ds_read_b128 v[200:203], v183 offset:38912
	ds_read_b128 v[204:207], v183 offset:39936
	global_load_lds_dwordx4 v[226:227], off
	v_lshl_add_u64 v[226:227], s[56:57], 0, v[168:169]
	s_mov_b32 m0, s59
	s_nop 0
	global_load_lds_dwordx4 v[226:227], off
	s_waitcnt vmcnt(8)
	s_waitcnt lgkmcnt(0)
	s_barrier
	s_setprio 1
	s_waitcnt lgkmcnt(0)
	v_mfma_f32_16x16x32_bf16 v[158:161], v[60:63], v[162:165], v[158:161]
	v_mfma_f32_16x16x32_bf16 v[154:157], v[72:75], v[162:165], v[154:157]
	v_mfma_f32_16x16x32_bf16 v[142:145], v[60:63], v[184:187], v[142:145]
	v_mfma_f32_16x16x32_bf16 v[138:141], v[72:75], v[184:187], v[138:141]
	v_mfma_f32_16x16x32_bf16 v[126:129], v[60:63], v[192:195], v[126:129]
	v_mfma_f32_16x16x32_bf16 v[122:125], v[72:75], v[192:195], v[122:125]
	v_mfma_f32_16x16x32_bf16 v[110:113], v[60:63], v[200:203], v[110:113]
	v_mfma_f32_16x16x32_bf16 v[106:109], v[72:75], v[200:203], v[106:109]
	v_mfma_f32_16x16x32_bf16 v[158:161], v[64:67], v[176:179], v[158:161]
	v_mfma_f32_16x16x32_bf16 v[154:157], v[76:79], v[176:179], v[154:157]
	v_mfma_f32_16x16x32_bf16 v[142:145], v[64:67], v[188:191], v[142:145]
	v_mfma_f32_16x16x32_bf16 v[138:141], v[76:79], v[188:191], v[138:141]
	v_mfma_f32_16x16x32_bf16 v[126:129], v[64:67], v[196:199], v[126:129]
	v_mfma_f32_16x16x32_bf16 v[122:125], v[76:79], v[196:199], v[122:125]
	v_mfma_f32_16x16x32_bf16 v[110:113], v[64:67], v[204:207], v[110:113]
	v_mfma_f32_16x16x32_bf16 v[106:109], v[76:79], v[204:207], v[106:109]
	v_mfma_f32_16x16x32_bf16 v[150:153], v[82:85], v[162:165], v[150:153]
	v_mfma_f32_16x16x32_bf16 v[146:149], v[90:93], v[162:165], v[146:149]
	v_mfma_f32_16x16x32_bf16 v[134:137], v[82:85], v[184:187], v[134:137]
	v_mfma_f32_16x16x32_bf16 v[130:133], v[90:93], v[184:187], v[130:133]
	v_mfma_f32_16x16x32_bf16 v[118:121], v[82:85], v[192:195], v[118:121]
	v_mfma_f32_16x16x32_bf16 v[114:117], v[90:93], v[192:195], v[114:117]
	v_mfma_f32_16x16x32_bf16 v[102:105], v[82:85], v[200:203], v[102:105]
	v_mfma_f32_16x16x32_bf16 v[98:101], v[90:93], v[200:203], v[98:101]
	v_mfma_f32_16x16x32_bf16 v[150:153], v[86:89], v[176:179], v[150:153]
	v_mfma_f32_16x16x32_bf16 v[146:149], v[94:97], v[176:179], v[146:149]
	v_mfma_f32_16x16x32_bf16 v[134:137], v[86:89], v[188:191], v[134:137]
	v_mfma_f32_16x16x32_bf16 v[130:133], v[94:97], v[188:191], v[130:133]
	v_mfma_f32_16x16x32_bf16 v[118:121], v[86:89], v[196:199], v[118:121]
	v_mfma_f32_16x16x32_bf16 v[114:117], v[94:97], v[196:199], v[114:117]
	v_mfma_f32_16x16x32_bf16 v[102:105], v[86:89], v[204:207], v[102:105]
	v_mfma_f32_16x16x32_bf16 v[98:101], v[94:97], v[204:207], v[98:101]
	s_setprio 0
	s_barrier
; #define PG8_STAGE(bufoff, gbase, voff) do { _Pragma("unroll") for (int _i = 0; _i < 2; ++_i) \
;         __builtin_amdgcn_global_load_lds((const unsigned*)((const char*)(gbase) + (voff)[_i]), (PG8_LAS unsigned*)(lds + (bufoff) + ldsw + _i * 8192), 16, 0, 0); } while (0)
; #define PG8_LDA(dst, b, h) do { _Pragma("unroll") for (int m = 0; m < 4; ++m) _Pragma("unroll") for (int k = 0; k < 2; ++k) dst[m][k] = *(const PG8_LAS bf16x8*)(lds + PG8_SA(b, h) + aoff + m * 2048 + k * 1024); } while (0)
; #define PG8_MMA(ai, bj, At, Bt) do { __builtin_amdgcn_s_setprio(1); _Pragma("unroll") for (int m = 0; m < 4; ++m) _Pragma("unroll") for (int n = 0; n < 2; ++n) _Pragma("unroll") for (int k = 0; k < 2; ++k) \
;         acc[ai][bj][m][n] = __builtin_amdgcn_mfma_f32_16x16x32_bf16(Bt[n][k], At[m][k], acc[ai][bj][m][n], 0, 0, 0); __builtin_amdgcn_s_setprio(0); } while (0)
; #define PG8_WAIT_V(n) asm volatile("s_waitcnt vmcnt(" #n ")" ::: "memory")
; #define PG8_WAIT_L(n) asm volatile("s_waitcnt lgkmcnt(" #n ")" ::: "memory")
; #define PG8_BAR __builtin_amdgcn_s_barrier()
; #define PG8_SCHED __builtin_amdgcn_sched_barrier(0)
; template <class Epi, class Sched, bool ALIGN_EPI = false, bool SP2 = false>
; __device__ __forceinline__ void gemm_phase(PG8_LAS unsigned char* lds, const Gemm g, const Sched& S, const Epi& E, int tid_in) {
;     ...
;         for (int t = 0; t < nt; t += 2) {
;             const bool last = (t == nt - 2);
;             const char* a1 = cA + (size_t)(t + 1) * kstep;
;             const char* a2 = last ? nA : cA + (size_t)(t + 2) * kstep; const char* b2 = last ? nB : cB + (size_t)(t + 2) * kstep;
;     ...
;             PG8_LDA(At, 1, 1); PG8_STAGE(PG8_SB(1, 0), b3, voffB); PG8_STAGE(PG8_SB(1, 1), b3 + hstep, voffB); PG8_STAGE(PG8_SA(1, 0), a3, voffA);
;             PG8_WAIT_V(8); PG8_WAIT_L(0); PG8_BAR; PG8_MMA(1, 0, At, B0); PG8_MMA(1, 1, At, B1); PG8_BAR; PG8_SCHED;
	s_add_i32 s56, s72, s17
	v_lshl_add_u64 v[208:209], v[208:209], 0, s[6:7]
	s_mov_b32 m0, s56
	ds_read_b128 v[162:165], v183 offset:49152
	ds_read_b128 v[176:179], v183 offset:50176
	ds_read_b128 v[184:187], v183 offset:51200
	ds_read_b128 v[188:191], v183 offset:52224
	ds_read_b128 v[192:195], v183 offset:53248
	ds_read_b128 v[196:199], v183 offset:54272
	ds_read_b128 v[200:203], v183 offset:55296
	ds_read_b128 v[204:207], v183 offset:56320
	global_load_lds_dwordx4 v[208:209], off
	s_add_i32 m0, s56, 0x2000
	s_add_u32 s54, s54, 0x40080
	v_lshl_add_u64 v[208:209], v[210:211], 0, s[6:7]
	s_addc_u32 s55, s55, 0
	s_add_i32 s56, s73, s17
	global_load_lds_dwordx4 v[208:209], off
	v_lshl_add_u64 v[208:209], s[54:55], 0, v[80:81]
	s_mov_b32 m0, s56
	s_nop 0
	global_load_lds_dwordx4 v[208:209], off
	v_lshl_add_u64 v[208:209], s[54:55], 0, v[170:171]
	s_add_i32 m0, s56, 0x2000
	s_nop 0
	global_load_lds_dwordx4 v[208:209], off
	v_lshl_add_u64 v[208:209], v[212:213], 0, s[6:7]
	s_mov_b32 m0, s62
	s_nop 0
	global_load_lds_dwordx4 v[208:209], off
	v_lshl_add_u64 v[208:209], v[214:215], 0, s[6:7]
	s_mov_b32 m0, s63
	s_nop 0
	global_load_lds_dwordx4 v[208:209], off
	s_waitcnt vmcnt(8)
	s_waitcnt lgkmcnt(0)
	s_barrier
	s_setprio 1
	s_waitcnt lgkmcnt(0)
	v_mfma_f32_16x16x32_bf16 v[68:71], v[60:63], v[162:165], v[68:71]
	v_mfma_f32_16x16x32_bf16 v[56:59], v[72:75], v[162:165], v[56:59]
	v_mfma_f32_16x16x32_bf16 v[44:47], v[60:63], v[184:187], v[44:47]
	v_mfma_f32_16x16x32_bf16 v[40:43], v[72:75], v[184:187], v[40:43]
	v_mfma_f32_16x16x32_bf16 v[28:31], v[60:63], v[192:195], v[28:31]
	v_mfma_f32_16x16x32_bf16 v[24:27], v[72:75], v[192:195], v[24:27]
	v_mfma_f32_16x16x32_bf16 v[12:15], v[60:63], v[200:203], v[12:15]
	v_mfma_f32_16x16x32_bf16 v[8:11], v[72:75], v[200:203], v[8:11]
	v_mfma_f32_16x16x32_bf16 v[68:71], v[64:67], v[176:179], v[68:71]
	v_mfma_f32_16x16x32_bf16 v[56:59], v[76:79], v[176:179], v[56:59]
	v_mfma_f32_16x16x32_bf16 v[44:47], v[64:67], v[188:191], v[44:47]
	v_mfma_f32_16x16x32_bf16 v[40:43], v[76:79], v[188:191], v[40:43]
	v_mfma_f32_16x16x32_bf16 v[28:31], v[64:67], v[196:199], v[28:31]
	v_mfma_f32_16x16x32_bf16 v[24:27], v[76:79], v[196:199], v[24:27]
	v_mfma_f32_16x16x32_bf16 v[12:15], v[64:67], v[204:207], v[12:15]
	v_mfma_f32_16x16x32_bf16 v[8:11], v[76:79], v[204:207], v[8:11]
	v_mfma_f32_16x16x32_bf16 v[52:55], v[82:85], v[162:165], v[52:55]
	v_mfma_f32_16x16x32_bf16 v[48:51], v[90:93], v[162:165], v[48:51]
	v_mfma_f32_16x16x32_bf16 v[36:39], v[82:85], v[184:187], v[36:39]
	v_mfma_f32_16x16x32_bf16 v[32:35], v[90:93], v[184:187], v[32:35]
	v_mfma_f32_16x16x32_bf16 v[20:23], v[82:85], v[192:195], v[20:23]
	v_mfma_f32_16x16x32_bf16 v[16:19], v[90:93], v[192:195], v[16:19]
	v_mfma_f32_16x16x32_bf16 v[4:7], v[82:85], v[200:203], v[4:7]
	v_mfma_f32_16x16x32_bf16 v[0:3], v[90:93], v[200:203], v[0:3]
	v_mfma_f32_16x16x32_bf16 v[52:55], v[86:89], v[176:179], v[52:55]
	v_mfma_f32_16x16x32_bf16 v[48:51], v[94:97], v[176:179], v[48:51]
	v_mfma_f32_16x16x32_bf16 v[36:39], v[86:89], v[188:191], v[36:39]
	v_mfma_f32_16x16x32_bf16 v[32:35], v[94:97], v[188:191], v[32:35]
	v_mfma_f32_16x16x32_bf16 v[20:23], v[86:89], v[196:199], v[20:23]
	v_mfma_f32_16x16x32_bf16 v[16:19], v[94:97], v[196:199], v[16:19]
	v_mfma_f32_16x16x32_bf16 v[4:7], v[86:89], v[204:207], v[4:7]
	v_mfma_f32_16x16x32_bf16 v[0:3], v[94:97], v[204:207], v[0:3]
	s_setprio 0
	s_barrier
	s_add_i32 s71, s71, 2
	s_add_u32 s52, s52, 0x100
	s_addc_u32 s53, s53, 0
	s_add_u32 s69, s69, 0x100
	s_addc_u32 s70, s70, 0
	s_cmp_gt_u32 s71, 13
	s_cbranch_scc0 .LBB0_1601
	s_and_b64 vcc, exec, s[40:41]
	s_cbranch_vccz .LBB0_1604
	s_barrier

; #define PG8_STAGE(bufoff, gbase, voff) do { _Pragma("unroll") for (int _i = 0; _i < 2; ++_i) \
;         __builtin_amdgcn_global_load_lds((const unsigned*)((const char*)(gbase) + (voff)[_i]), (PG8_LAS unsigned*)(lds + (bufoff) + ldsw + _i * 8192), 16, 0, 0); } while (0)
; #define PG8_LDA(dst, b, h) do { _Pragma("unroll") for (int m = 0; m < 4; ++m) _Pragma("unroll") for (int k = 0; k < 2; ++k) dst[m][k] = *(const PG8_LAS bf16x8*)(lds + PG8_SA(b, h) + aoff + m * 2048 + k * 1024); } while (0)
; #define PG8_LDB(dst, b, h) do { _Pragma("unroll") for (int n = 0; n < 2; ++n) _Pragma("unroll") for (int k = 0; k < 2; ++k) dst[n][k] = *(const PG8_LAS bf16x8*)(lds + PG8_SB(b, h) + boff + n * 2048 + k * 1024); } while (0)
; #define PG8_MMA(ai, bj, At, Bt) do { __builtin_amdgcn_s_setprio(1); _Pragma("unroll") for (int m = 0; m < 4; ++m) _Pragma("unroll") for (int n = 0; n < 2; ++n) _Pragma("unroll") for (int k = 0; k < 2; ++k) \
;         acc[ai][bj][m][n] = __builtin_amdgcn_mfma_f32_16x16x32_bf16(Bt[n][k], At[m][k], acc[ai][bj][m][n], 0, 0, 0); __builtin_amdgcn_s_setprio(0); } while (0)
; #define PG8_WAIT_V(n) asm volatile("s_waitcnt vmcnt(" #n ")" ::: "memory")
; #define PG8_BAR __builtin_amdgcn_s_barrier()
; template <class Epi, class Sched, bool ALIGN_EPI = false, bool SP2 = false>
; __device__ __forceinline__ void gemm_phase(PG8_LAS unsigned char* lds, const Gemm g, const Sched& S, const Epi& E, int tid_in) {
;     ...
;         for (int t = 0; t < nt; t += 2) {
;             const bool last = (t == nt - 2);
;             const char* a1 = cA + (size_t)(t + 1) * kstep;
;             const char* a2 = last ? nA : cA + (size_t)(t + 2) * kstep; const char* b2 = last ? nB : cB + (size_t)(t + 2) * kstep;
;             const char* a3 = a2 + kstep; const char* b3 = b2 + kstep;
;             if (last && has_next) S.a_ready(nxt);
;             if constexpr (SP2) {
;             PG8_LDB(B0, 0, 0); PG8_LDB(B1, 0, 1); PG8_SCHED; PG8_LDA(At, 0, 0); PG8_STAGE(PG8_SA(1, 1), a1 + hstep, voffA);
;             PG8_WAIT_V(8); PG8_WAIT_L(0); PG8_BAR; PG8_MMA(0, 0, At, B0); PG8_MMA(0, 1, At, B1); PG8_BAR; PG8_SCHED;
;             PG8_LDA(At, 0, 1); PG8_STAGE(PG8_SB(0, 0), b2, voffB); PG8_STAGE(PG8_SB(0, 1), b2 + hstep, voffB); PG8_STAGE(PG8_SA(0, 0), a2, voffA);
;             PG8_WAIT_V(8); PG8_WAIT_L(0); PG8_BAR; PG8_MMA(1, 0, At, B0); PG8_MMA(1, 1, At, B1); PG8_BAR; PG8_SCHED;
.LBB0_1689:
	s_add_u32 s4, s2, 0x100
	s_addc_u32 s5, s3, 0
	s_add_i32 s65, 0, 0x10000
	s_cmp_eq_u32 s43, 40
	s_cselect_b32 s41, s61, s5
	s_cselect_b32 s40, s60, s4
	s_cselect_b32 s9, s63, s1
	s_cselect_b32 s8, s62, s0
	s_add_i32 s77, 0, 0x14000
	v_add_u32_e32 v126, s65, v202
	v_add_u32_e32 v158, s77, v202
	ds_read_b128 v[90:93], v126
	ds_read_b128 v[102:105], v126 offset:1024
	ds_read_b128 v[114:117], v126 offset:2048
	ds_read_b128 v[126:129], v126 offset:3072
	ds_read_b128 v[138:141], v158
	ds_read_b128 v[150:153], v158 offset:1024
	ds_read_b128 v[154:157], v158 offset:2048
	ds_read_b128 v[158:161], v158 offset:3072
	v_lshl_add_u64 v[208:209], s[2:3], 0, v[168:169]
	s_add_i32 m0, s15, 0xc000
	ds_read_b128 v[172:175], v203
	ds_read_b128 v[176:179], v203 offset:1024
	ds_read_b128 v[180:183], v203 offset:2048
	ds_read_b128 v[184:187], v203 offset:3072
	ds_read_b128 v[188:191], v203 offset:4096
	ds_read_b128 v[192:195], v203 offset:5120
	ds_read_b128 v[196:199], v203 offset:6144
	ds_read_b128 v[204:207], v203 offset:7168
	global_load_lds_dwordx4 v[208:209], off
	v_lshl_add_u64 v[208:209], s[2:3], 0, v[170:171]
	s_add_i32 m0, s15, 0xe000
	s_nop 0
	global_load_lds_dwordx4 v[208:209], off
	s_waitcnt vmcnt(8)
	s_waitcnt lgkmcnt(0)
	s_barrier
	s_setprio 1
	s_waitcnt lgkmcnt(0)
	v_mfma_f32_16x16x32_bf16 v[146:149], v[90:93], v[172:175], v[146:149]
	v_mfma_f32_16x16x32_bf16 v[142:145], v[114:117], v[172:175], v[142:145]
	v_mfma_f32_16x16x32_bf16 v[122:125], v[90:93], v[180:183], v[122:125]
	v_mfma_f32_16x16x32_bf16 v[118:121], v[114:117], v[180:183], v[118:121]
	v_mfma_f32_16x16x32_bf16 v[98:101], v[90:93], v[188:191], v[98:101]
	v_mfma_f32_16x16x32_bf16 v[94:97], v[114:117], v[188:191], v[94:97]
	v_mfma_f32_16x16x32_bf16 v[76:79], v[90:93], v[196:199], v[76:79]
	v_mfma_f32_16x16x32_bf16 v[72:75], v[114:117], v[196:199], v[72:75]
	v_mfma_f32_16x16x32_bf16 v[146:149], v[102:105], v[176:179], v[146:149]
	v_mfma_f32_16x16x32_bf16 v[142:145], v[126:129], v[176:179], v[142:145]
	v_mfma_f32_16x16x32_bf16 v[122:125], v[102:105], v[184:187], v[122:125]
	v_mfma_f32_16x16x32_bf16 v[118:121], v[126:129], v[184:187], v[118:121]
	v_mfma_f32_16x16x32_bf16 v[98:101], v[102:105], v[192:195], v[98:101]
	v_mfma_f32_16x16x32_bf16 v[94:97], v[126:129], v[192:195], v[94:97]
	v_mfma_f32_16x16x32_bf16 v[76:79], v[102:105], v[204:207], v[76:79]
	v_mfma_f32_16x16x32_bf16 v[72:75], v[126:129], v[204:207], v[72:75]
	v_mfma_f32_16x16x32_bf16 v[134:137], v[138:141], v[172:175], v[134:137]
	v_mfma_f32_16x16x32_bf16 v[130:133], v[154:157], v[172:175], v[130:133]
	v_mfma_f32_16x16x32_bf16 v[110:113], v[138:141], v[180:183], v[110:113]
	v_mfma_f32_16x16x32_bf16 v[106:109], v[154:157], v[180:183], v[106:109]
	v_mfma_f32_16x16x32_bf16 v[86:89], v[138:141], v[188:191], v[86:89]
	v_mfma_f32_16x16x32_bf16 v[82:85], v[154:157], v[188:191], v[82:85]
	v_mfma_f32_16x16x32_bf16 v[68:71], v[138:141], v[196:199], v[68:71]
	v_mfma_f32_16x16x32_bf16 v[64:67], v[154:157], v[196:199], v[64:67]
	v_mfma_f32_16x16x32_bf16 v[134:137], v[150:153], v[176:179], v[134:137]
	v_mfma_f32_16x16x32_bf16 v[130:133], v[158:161], v[176:179], v[130:133]
	v_mfma_f32_16x16x32_bf16 v[110:113], v[150:153], v[184:187], v[110:113]
	v_mfma_f32_16x16x32_bf16 v[106:109], v[158:161], v[184:187], v[106:109]
	v_mfma_f32_16x16x32_bf16 v[86:89], v[150:153], v[192:195], v[86:89]
	v_mfma_f32_16x16x32_bf16 v[82:85], v[158:161], v[192:195], v[82:85]
	v_mfma_f32_16x16x32_bf16 v[68:71], v[150:153], v[204:207], v[68:71]
	v_mfma_f32_16x16x32_bf16 v[64:67], v[158:161], v[204:207], v[64:67]
	s_setprio 0
	s_barrier
	s_add_i32 s2, s65, s14
	v_lshl_add_u64 v[208:209], s[8:9], 0, v[80:81]
	s_mov_b32 m0, s2
	ds_read_b128 v[172:175], v203 offset:16384
	ds_read_b128 v[176:179], v203 offset:17408
	ds_read_b128 v[180:183], v203 offset:18432
	ds_read_b128 v[184:187], v203 offset:19456
	ds_read_b128 v[188:191], v203 offset:20480
	ds_read_b128 v[192:195], v203 offset:21504
	ds_read_b128 v[196:199], v203 offset:22528
	ds_read_b128 v[204:207], v203 offset:23552
	global_load_lds_dwordx4 v[208:209], off
	s_add_i32 m0, s2, 0x2000
	s_add_u32 s2, s8, 0xb0000
	v_lshl_add_u64 v[210:211], s[8:9], 0, v[166:167]
	s_addc_u32 s3, s9, 0
	s_add_i32 s65, s77, s14
	global_load_lds_dwordx4 v[210:211], off
	v_lshl_add_u64 v[212:213], s[2:3], 0, v[80:81]
	s_mov_b32 m0, s65
	v_lshl_add_u64 v[214:215], s[40:41], 0, v[164:165]
	global_load_lds_dwordx4 v[212:213], off
	v_lshl_add_u64 v[212:213], s[2:3], 0, v[166:167]
	s_add_i32 m0, s65, 0x2000
	s_nop 0
	global_load_lds_dwordx4 v[212:213], off
	v_lshl_add_u64 v[212:213], s[40:41], 0, v[162:163]
	s_mov_b32 m0, s15
	s_nop 0
	global_load_lds_dwordx4 v[212:213], off
	s_mov_b32 m0, s16
	s_nop 0
	global_load_lds_dwordx4 v[214:215], off
	s_waitcnt vmcnt(8)
	s_waitcnt lgkmcnt(0)
	s_barrier
; #define PG8_STAGE(bufoff, gbase, voff) do { _Pragma("unroll") for (int _i = 0; _i < 2; ++_i) \
;         __builtin_amdgcn_global_load_lds((const unsigned*)((const char*)(gbase) + (voff)[_i]), (PG8_LAS unsigned*)(lds + (bufoff) + ldsw + _i * 8192), 16, 0, 0); } while (0)
; #define PG8_LDA(dst, b, h) do { _Pragma("unroll") for (int m = 0; m < 4; ++m) _Pragma("unroll") for (int k = 0; k < 2; ++k) dst[m][k] = *(const PG8_LAS bf16x8*)(lds + PG8_SA(b, h) + aoff + m * 2048 + k * 1024); } while (0)
; #define PG8_LDB(dst, b, h) do { _Pragma("unroll") for (int n = 0; n < 2; ++n) _Pragma("unroll") for (int k = 0; k < 2; ++k) dst[n][k] = *(const PG8_LAS bf16x8*)(lds + PG8_SB(b, h) + boff + n * 2048 + k * 1024); } while (0)
; #define PG8_MMA(ai, bj, At, Bt) do { __builtin_amdgcn_s_setprio(1); _Pragma("unroll") for (int m = 0; m < 4; ++m) _Pragma("unroll") for (int n = 0; n < 2; ++n) _Pragma("unroll") for (int k = 0; k < 2; ++k) \
;         acc[ai][bj][m][n] = __builtin_amdgcn_mfma_f32_16x16x32_bf16(Bt[n][k], At[m][k], acc[ai][bj][m][n], 0, 0, 0); __builtin_amdgcn_s_setprio(0); } while (0)
; #define PG8_WAIT_V(n) asm volatile("s_waitcnt vmcnt(" #n ")" ::: "memory")
; #define PG8_WAIT_L(n) asm volatile("s_waitcnt lgkmcnt(" #n ")" ::: "memory")
; #define PG8_BAR __builtin_amdgcn_s_barrier()
; #define PG8_SCHED __builtin_amdgcn_sched_barrier(0)
; template <class Epi, class Sched, bool ALIGN_EPI = false, bool SP2 = false>
; __device__ __forceinline__ void gemm_phase(PG8_LAS unsigned char* lds, const Gemm g, const Sched& S, const Epi& E, int tid_in) {
;     ...
;             PG8_WAIT_V(8); PG8_WAIT_L(0); PG8_BAR; PG8_MMA(1, 0, At, B0); PG8_MMA(1, 1, At, B1); PG8_BAR; PG8_SCHED;
;             PG8_LDB(B0, 1, 0); PG8_LDB(B1, 1, 1); PG8_SCHED; PG8_LDA(At, 1, 0); PG8_STAGE(PG8_SA(0, 1), a2 + hstep, voffA);
;             PG8_WAIT_V(8); PG8_WAIT_L(0); PG8_BAR; PG8_MMA(0, 0, At, B0); PG8_MMA(0, 1, At, B1); PG8_BAR; PG8_SCHED;
	s_setprio 1
	s_waitcnt lgkmcnt(0)
	v_mfma_f32_16x16x32_bf16 v[60:63], v[90:93], v[172:175], v[60:63]
	v_mfma_f32_16x16x32_bf16 v[56:59], v[114:117], v[172:175], v[56:59]
	v_mfma_f32_16x16x32_bf16 v[44:47], v[90:93], v[180:183], v[44:47]
	v_mfma_f32_16x16x32_bf16 v[40:43], v[114:117], v[180:183], v[40:43]
	v_mfma_f32_16x16x32_bf16 v[28:31], v[90:93], v[188:191], v[28:31]
	v_mfma_f32_16x16x32_bf16 v[24:27], v[114:117], v[188:191], v[24:27]
	v_mfma_f32_16x16x32_bf16 v[12:15], v[90:93], v[196:199], v[12:15]
	v_mfma_f32_16x16x32_bf16 v[8:11], v[114:117], v[196:199], v[8:11]
	v_mfma_f32_16x16x32_bf16 v[60:63], v[102:105], v[176:179], v[60:63]
	v_mfma_f32_16x16x32_bf16 v[56:59], v[126:129], v[176:179], v[56:59]
	v_mfma_f32_16x16x32_bf16 v[44:47], v[102:105], v[184:187], v[44:47]
	v_mfma_f32_16x16x32_bf16 v[40:43], v[126:129], v[184:187], v[40:43]
	v_mfma_f32_16x16x32_bf16 v[28:31], v[102:105], v[192:195], v[28:31]
	v_mfma_f32_16x16x32_bf16 v[24:27], v[126:129], v[192:195], v[24:27]
	v_mfma_f32_16x16x32_bf16 v[12:15], v[102:105], v[204:207], v[12:15]
	v_mfma_f32_16x16x32_bf16 v[8:11], v[126:129], v[204:207], v[8:11]
	v_mfma_f32_16x16x32_bf16 v[52:55], v[138:141], v[172:175], v[52:55]
	v_mfma_f32_16x16x32_bf16 v[48:51], v[154:157], v[172:175], v[48:51]
	v_mfma_f32_16x16x32_bf16 v[36:39], v[138:141], v[180:183], v[36:39]
	v_mfma_f32_16x16x32_bf16 v[32:35], v[154:157], v[180:183], v[32:35]
	v_mfma_f32_16x16x32_bf16 v[20:23], v[138:141], v[188:191], v[20:23]
	v_mfma_f32_16x16x32_bf16 v[16:19], v[154:157], v[188:191], v[16:19]
	v_mfma_f32_16x16x32_bf16 v[4:7], v[138:141], v[196:199], v[4:7]
	v_mfma_f32_16x16x32_bf16 v[0:3], v[154:157], v[196:199], v[0:3]
	v_mfma_f32_16x16x32_bf16 v[52:55], v[150:153], v[176:179], v[52:55]
	v_mfma_f32_16x16x32_bf16 v[48:51], v[158:161], v[176:179], v[48:51]
	v_mfma_f32_16x16x32_bf16 v[36:39], v[150:153], v[184:187], v[36:39]
	v_mfma_f32_16x16x32_bf16 v[32:35], v[158:161], v[184:187], v[32:35]
	v_mfma_f32_16x16x32_bf16 v[20:23], v[150:153], v[192:195], v[20:23]
	v_mfma_f32_16x16x32_bf16 v[16:19], v[158:161], v[192:195], v[16:19]
	v_mfma_f32_16x16x32_bf16 v[4:7], v[150:153], v[204:207], v[4:7]
	v_mfma_f32_16x16x32_bf16 v[0:3], v[158:161], v[204:207], v[0:3]
	s_setprio 0
	s_barrier
	s_add_i32 s65, 0, 0x18000
	s_add_i32 s77, 0, 0x1c000
	v_add_u32_e32 v126, s65, v202
	v_add_u32_e32 v158, s77, v202
	ds_read_b128 v[90:93], v126
	ds_read_b128 v[102:105], v126 offset:1024
	ds_read_b128 v[114:117], v126 offset:2048
	ds_read_b128 v[126:129], v126 offset:3072
	ds_read_b128 v[138:141], v158
	ds_read_b128 v[150:153], v158 offset:1024
	ds_read_b128 v[154:157], v158 offset:2048
	ds_read_b128 v[158:161], v158 offset:3072
	s_add_u32 s2, s40, 0xb0000
	s_addc_u32 s3, s41, 0
	s_mov_b32 m0, s17
	v_lshl_add_u64 v[226:227], s[2:3], 0, v[162:163]
	ds_read_b128 v[172:175], v203 offset:32768
	ds_read_b128 v[176:179], v203 offset:33792
	ds_read_b128 v[180:183], v203 offset:34816
	ds_read_b128 v[184:187], v203 offset:35840
	ds_read_b128 v[188:191], v203 offset:36864
	ds_read_b128 v[192:195], v203 offset:37888
	ds_read_b128 v[196:199], v203 offset:38912
	ds_read_b128 v[204:207], v203 offset:39936
	global_load_lds_dwordx4 v[226:227], off
	v_lshl_add_u64 v[226:227], s[2:3], 0, v[164:165]
	s_mov_b32 m0, s18
	s_nop 0
	global_load_lds_dwordx4 v[226:227], off
	s_waitcnt vmcnt(8)
	s_waitcnt lgkmcnt(0)
	s_barrier
	s_setprio 1
	s_waitcnt lgkmcnt(0)
	v_mfma_f32_16x16x32_bf16 v[146:149], v[90:93], v[172:175], v[146:149]
	v_mfma_f32_16x16x32_bf16 v[142:145], v[114:117], v[172:175], v[142:145]
	v_mfma_f32_16x16x32_bf16 v[122:125], v[90:93], v[180:183], v[122:125]
	v_mfma_f32_16x16x32_bf16 v[118:121], v[114:117], v[180:183], v[118:121]
	v_mfma_f32_16x16x32_bf16 v[98:101], v[90:93], v[188:191], v[98:101]
	v_mfma_f32_16x16x32_bf16 v[94:97], v[114:117], v[188:191], v[94:97]
	v_mfma_f32_16x16x32_bf16 v[76:79], v[90:93], v[196:199], v[76:79]
	v_mfma_f32_16x16x32_bf16 v[72:75], v[114:117], v[196:199], v[72:75]
	v_mfma_f32_16x16x32_bf16 v[146:149], v[102:105], v[176:179], v[146:149]
	v_mfma_f32_16x16x32_bf16 v[142:145], v[126:129], v[176:179], v[142:145]
	v_mfma_f32_16x16x32_bf16 v[122:125], v[102:105], v[184:187], v[122:125]
	v_mfma_f32_16x16x32_bf16 v[118:121], v[126:129], v[184:187], v[118:121]
	v_mfma_f32_16x16x32_bf16 v[98:101], v[102:105], v[192:195], v[98:101]
	v_mfma_f32_16x16x32_bf16 v[94:97], v[126:129], v[192:195], v[94:97]
	v_mfma_f32_16x16x32_bf16 v[76:79], v[102:105], v[204:207], v[76:79]
	v_mfma_f32_16x16x32_bf16 v[72:75], v[126:129], v[204:207], v[72:75]
	v_mfma_f32_16x16x32_bf16 v[134:137], v[138:141], v[172:175], v[134:137]
	v_mfma_f32_16x16x32_bf16 v[130:133], v[154:157], v[172:175], v[130:133]
	v_mfma_f32_16x16x32_bf16 v[110:113], v[138:141], v[180:183], v[110:113]
	v_mfma_f32_16x16x32_bf16 v[106:109], v[154:157], v[180:183], v[106:109]
	v_mfma_f32_16x16x32_bf16 v[86:89], v[138:141], v[188:191], v[86:89]
	v_mfma_f32_16x16x32_bf16 v[82:85], v[154:157], v[188:191], v[82:85]
	v_mfma_f32_16x16x32_bf16 v[68:71], v[138:141], v[196:199], v[68:71]
	v_mfma_f32_16x16x32_bf16 v[64:67], v[154:157], v[196:199], v[64:67]
	v_mfma_f32_16x16x32_bf16 v[134:137], v[150:153], v[176:179], v[134:137]
	v_mfma_f32_16x16x32_bf16 v[130:133], v[158:161], v[176:179], v[130:133]
	v_mfma_f32_16x16x32_bf16 v[110:113], v[150:153], v[184:187], v[110:113]
	v_mfma_f32_16x16x32_bf16 v[106:109], v[158:161], v[184:187], v[106:109]
	v_mfma_f32_16x16x32_bf16 v[86:89], v[150:153], v[192:195], v[86:89]
	v_mfma_f32_16x16x32_bf16 v[82:85], v[158:161], v[192:195], v[82:85]
	v_mfma_f32_16x16x32_bf16 v[68:71], v[150:153], v[204:207], v[68:71]
	v_mfma_f32_16x16x32_bf16 v[64:67], v[158:161], v[204:207], v[64:67]
	s_setprio 0
	s_barrier
; #define PG8_STAGE(bufoff, gbase, voff) do { _Pragma("unroll") for (int _i = 0; _i < 2; ++_i) \
;         __builtin_amdgcn_global_load_lds((const unsigned*)((const char*)(gbase) + (voff)[_i]), (PG8_LAS unsigned*)(lds + (bufoff) + ldsw + _i * 8192), 16, 0, 0); } while (0)
; #define PG8_LDA(dst, b, h) do { _Pragma("unroll") for (int m = 0; m < 4; ++m) _Pragma("unroll") for (int k = 0; k < 2; ++k) dst[m][k] = *(const PG8_LAS bf16x8*)(lds + PG8_SA(b, h) + aoff + m * 2048 + k * 1024); } while (0)
; #define PG8_MMA(ai, bj, At, Bt) do { __builtin_amdgcn_s_setprio(1); _Pragma("unroll") for (int m = 0; m < 4; ++m) _Pragma("unroll") for (int n = 0; n < 2; ++n) _Pragma("unroll") for (int k = 0; k < 2; ++k) \
;         acc[ai][bj][m][n] = __builtin_amdgcn_mfma_f32_16x16x32_bf16(Bt[n][k], At[m][k], acc[ai][bj][m][n], 0, 0, 0); __builtin_amdgcn_s_setprio(0); } while (0)
; #define PG8_WAIT_V(n) asm volatile("s_waitcnt vmcnt(" #n ")" ::: "memory")
; #define PG8_WAIT_L(n) asm volatile("s_waitcnt lgkmcnt(" #n ")" ::: "memory")
; #define PG8_BAR __builtin_amdgcn_s_barrier()
; #define PG8_SCHED __builtin_amdgcn_sched_barrier(0)
; template <class Epi, class Sched, bool ALIGN_EPI = false, bool SP2 = false>
; __device__ __forceinline__ void gemm_phase(PG8_LAS unsigned char* lds, const Gemm g, const Sched& S, const Epi& E, int tid_in) {
;     ...
;         for (int t = 0; t < nt; t += 2) {
;             const bool last = (t == nt - 2);
;             const char* a1 = cA + (size_t)(t + 1) * kstep;
;             const char* a2 = last ? nA : cA + (size_t)(t + 2) * kstep; const char* b2 = last ? nB : cB + (size_t)(t + 2) * kstep;
;     ...
;             PG8_LDA(At, 1, 1); PG8_STAGE(PG8_SB(1, 0), b3, voffB); PG8_STAGE(PG8_SB(1, 1), b3 + hstep, voffB); PG8_STAGE(PG8_SA(1, 0), a3, voffA);
;             PG8_WAIT_V(8); PG8_WAIT_L(0); PG8_BAR; PG8_MMA(1, 0, At, B0); PG8_MMA(1, 1, At, B1); PG8_BAR; PG8_SCHED;
	s_add_i32 s2, s65, s14
	v_lshl_add_u64 v[208:209], v[208:209], 0, s[6:7]
	s_mov_b32 m0, s2
	ds_read_b128 v[172:175], v203 offset:49152
	ds_read_b128 v[176:179], v203 offset:50176
	ds_read_b128 v[180:183], v203 offset:51200
	ds_read_b128 v[184:187], v203 offset:52224
	ds_read_b128 v[188:191], v203 offset:53248
	ds_read_b128 v[192:195], v203 offset:54272
	ds_read_b128 v[196:199], v203 offset:55296
	ds_read_b128 v[204:207], v203 offset:56320
	global_load_lds_dwordx4 v[208:209], off
	s_add_i32 m0, s2, 0x2000
	s_add_u32 s2, s8, 0xb0080
	v_lshl_add_u64 v[208:209], v[210:211], 0, s[6:7]
	s_addc_u32 s3, s9, 0
	s_add_i32 s8, s77, s14
	global_load_lds_dwordx4 v[208:209], off
	v_lshl_add_u64 v[208:209], s[2:3], 0, v[80:81]
	s_mov_b32 m0, s8
	s_nop 0
	global_load_lds_dwordx4 v[208:209], off
	v_lshl_add_u64 v[208:209], s[2:3], 0, v[166:167]
	s_add_i32 m0, s8, 0x2000
	s_nop 0
	global_load_lds_dwordx4 v[208:209], off
	v_lshl_add_u64 v[208:209], v[212:213], 0, s[6:7]
	s_mov_b32 m0, s67
	s_nop 0
	global_load_lds_dwordx4 v[208:209], off
	v_lshl_add_u64 v[208:209], v[214:215], 0, s[6:7]
	s_mov_b32 m0, s68
	s_nop 0
	global_load_lds_dwordx4 v[208:209], off
	s_waitcnt vmcnt(8)
	s_waitcnt lgkmcnt(0)
	s_barrier
	s_setprio 1
	s_waitcnt lgkmcnt(0)
	v_mfma_f32_16x16x32_bf16 v[60:63], v[90:93], v[172:175], v[60:63]
	v_mfma_f32_16x16x32_bf16 v[56:59], v[114:117], v[172:175], v[56:59]
	v_mfma_f32_16x16x32_bf16 v[44:47], v[90:93], v[180:183], v[44:47]
	v_mfma_f32_16x16x32_bf16 v[40:43], v[114:117], v[180:183], v[40:43]
	v_mfma_f32_16x16x32_bf16 v[28:31], v[90:93], v[188:191], v[28:31]
	v_mfma_f32_16x16x32_bf16 v[24:27], v[114:117], v[188:191], v[24:27]
	v_mfma_f32_16x16x32_bf16 v[12:15], v[90:93], v[196:199], v[12:15]
	v_mfma_f32_16x16x32_bf16 v[8:11], v[114:117], v[196:199], v[8:11]
	v_mfma_f32_16x16x32_bf16 v[60:63], v[102:105], v[176:179], v[60:63]
	v_mfma_f32_16x16x32_bf16 v[56:59], v[126:129], v[176:179], v[56:59]
	v_mfma_f32_16x16x32_bf16 v[44:47], v[102:105], v[184:187], v[44:47]
	v_mfma_f32_16x16x32_bf16 v[40:43], v[126:129], v[184:187], v[40:43]
	v_mfma_f32_16x16x32_bf16 v[28:31], v[102:105], v[192:195], v[28:31]
	v_mfma_f32_16x16x32_bf16 v[24:27], v[126:129], v[192:195], v[24:27]
	v_mfma_f32_16x16x32_bf16 v[12:15], v[102:105], v[204:207], v[12:15]
	v_mfma_f32_16x16x32_bf16 v[8:11], v[126:129], v[204:207], v[8:11]
	v_mfma_f32_16x16x32_bf16 v[52:55], v[138:141], v[172:175], v[52:55]
	v_mfma_f32_16x16x32_bf16 v[48:51], v[154:157], v[172:175], v[48:51]
	v_mfma_f32_16x16x32_bf16 v[36:39], v[138:141], v[180:183], v[36:39]
	v_mfma_f32_16x16x32_bf16 v[32:35], v[154:157], v[180:183], v[32:35]
	v_mfma_f32_16x16x32_bf16 v[20:23], v[138:141], v[188:191], v[20:23]
	v_mfma_f32_16x16x32_bf16 v[16:19], v[154:157], v[188:191], v[16:19]
	v_mfma_f32_16x16x32_bf16 v[4:7], v[138:141], v[196:199], v[4:7]
	v_mfma_f32_16x16x32_bf16 v[0:3], v[154:157], v[196:199], v[0:3]
	v_mfma_f32_16x16x32_bf16 v[52:55], v[150:153], v[176:179], v[52:55]
	v_mfma_f32_16x16x32_bf16 v[48:51], v[158:161], v[176:179], v[48:51]
	v_mfma_f32_16x16x32_bf16 v[36:39], v[150:153], v[184:187], v[36:39]
	v_mfma_f32_16x16x32_bf16 v[32:35], v[158:161], v[184:187], v[32:35]
	v_mfma_f32_16x16x32_bf16 v[20:23], v[150:153], v[192:195], v[20:23]
	v_mfma_f32_16x16x32_bf16 v[16:19], v[158:161], v[192:195], v[16:19]
	v_mfma_f32_16x16x32_bf16 v[4:7], v[150:153], v[204:207], v[4:7]
	v_mfma_f32_16x16x32_bf16 v[0:3], v[158:161], v[204:207], v[0:3]
	s_setprio 0
	s_barrier
	s_add_i32 s43, s43, 2
	s_add_u32 s0, s0, 0x100
	s_addc_u32 s1, s1, 0
	s_cmp_gt_u32 s43, 41
	s_mov_b64 s[2:3], s[4:5]
	s_cbranch_scc0 .LBB0_1689
	s_and_b64 vcc, exec, s[58:59]
	s_cbranch_vccz .LBB0_1692
	s_barrier
